# v85 + within-row butterfly steps of the gla_finalize and three row-phase wave sums done with DPP (bitwise identical) instead of LDS bpermute round trips; nt on the GDN scan output stores
# baseline (speedup 1.0000x reference)
; #define LAS __attribute__((address_space(3)))
; template <bool POST, bool PRE>
; __device__ __forceinline__ void row_core(const Params& P, const RowCfg& c, LAS float* vA, LAS float* vB, LAS float* vP, const bf16_t* RAW, const float* SSQ, bf16_t* H, int row, int lane, f32x4 (&v)[8]) {
;     const f32x4* xs = (const f32x4*)(c.xsrc + (size_t)row * DM) + lane;
; #pragma unroll
;     for (int j = 0; j < 8; ++j) v[j] = xs[64 * j];
;     if (POST) {
;         const u32x2* rs = (const u32x2*)(RAW + (size_t)row * DM) + lane;
;         float s = (lane < 32) ? SSQ[(size_t)row * 32 + lane] : 0.f; s = wave_sum(s);
;         const float rstd = rsqrtf(s * (1.0f / DM) + EPS);
;         f32x4* os = (f32x4*)(P.out + (size_t)row * DM) + lane;
; #pragma unroll
;         for (int j = 0; j < 8; ++j) { const u32x2 rb = rs[64 * j]; const f32x4 r = (f32x4){__uint_as_float(rb.x << 16), __uint_as_float(rb.x & 0xffff0000u), __uint_as_float(rb.y << 16), __uint_as_float(rb.y & 0xffff0000u)};
;             const f32x4 pv = *(const LAS f32x4*)(vP + j * 256 + lane * 4); v[j] += r * rstd * pv; os[64 * j] = v[j]; }
;     }
;     if (PRE) {
;         float s2 = 0.f;
; #pragma unroll
;         for (int j = 0; j < 8; ++j) s2 += (v[j][0] * v[j][0] + v[j][1] * v[j][1]) + (v[j][2] * v[j][2] + v[j][3] * v[j][3]);
;         s2 = wave_sum(s2);
;         const float rstd2 = rsqrtf(s2 * (1.0f / DM) + EPS);
;         u32x2* hs = (u32x2*)(H + (size_t)row * DM) + lane;
; #pragma unroll
;         for (int j = 0; j < 8; ++j) { const f32x4 a = *(const LAS f32x4*)(vA + j * 256 + lane * 4), b = *(const LAS f32x4*)(vB + j * 256 + lane * 4);
;             v[j] = v[j] * rstd2 * a + b; u32x2 w; w.x = cvt_pk_bf16(v[j][0], v[j][1]); w.y = cvt_pk_bf16(v[j][2], v[j][3]); hs[64 * j] = w; }
; template <bool POST, bool PRE, bool THIN>
; __device__ __forceinline__ void row_phase(const Ctx& F, const RowCfg c) {
;     ...
;         for (int row = gw; row < SEQ; row += 2 * NGW) {
;             f32x4 v0[8], v1[8];
;             const int rowB = row + NGW; const bool hasB = rowB < SEQ;
;             row_core<POST, PRE>(P, c, vA, vB, vP, RAW, SSQ, H, row, lane, v0);
;             if (hasB) row_core<POST, PRE>(P, c, vA, vB, vP, RAW, SSQ, H, rowB, lane, v1);
;             else {
; #pragma unroll
;                 for (int j = 0; j < 8; ++j) v1[j] = (f32x4){0.f, 0.f, 0.f, 0.f}; }
.LBB0_184:
	s_add_i32 s16, s14, s3
	s_cmpk_lt_i32 s16, 0x4000
	s_cselect_b64 s[18:19], -1, 0
	s_ashr_i32 s15, s14, 31
	s_lshl_b64 s[20:21], s[14:15], 13
	s_waitcnt lgkmcnt(0)
	v_lshl_add_u64 v[0:1], v[32:33], 0, s[20:21]
	global_load_dwordx4 v[28:31], v[0:1], off nt
	global_load_dwordx4 v[24:27], v[0:1], off offset:1024 nt
	global_load_dwordx4 v[20:23], v[0:1], off offset:2048 nt
	global_load_dwordx4 v[16:19], v[0:1], off offset:3072 nt
	v_add_co_u32_e32 v4, vcc, s22, v0
	s_lshl_b64 s[20:21], s[14:15], 12
	s_nop 0
	v_addc_co_u32_e32 v5, vcc, 0, v1, vcc
	global_load_dwordx4 v[12:15], v[4:5], off nt
	global_load_dwordx4 v[8:11], v[4:5], off offset:1024 nt
	global_load_dwordx4 v[0:3], v[4:5], off offset:3072 nt
	s_nop 0
	global_load_dwordx4 v[4:7], v[4:5], off offset:2048 nt
	v_lshl_add_u64 v[68:69], v[34:35], 0, s[20:21]
	v_mov_b32_e32 v61, 0
	v_mov_b32_e32 v62, 0
	v_mov_b32_e32 v63, 0
	v_mov_b32_e32 v64, 0
	v_mov_b32_e32 v65, 0
	s_cmpk_gt_i32 s16, 0x3fff
	v_mov_b32_e32 v74, 0
	v_mov_b32_e32 v75, 0
	v_mov_b32_e32 v70, 0
	v_mov_b32_e32 v71, 0
	v_mov_b32_e32 v84, 0
	v_mov_b32_e32 v85, 0
	v_mov_b32_e32 v82, 0
	v_mov_b32_e32 v83, 0
	s_waitcnt vmcnt(7)
	v_mov_b32_e32 v40, v29
	s_waitcnt vmcnt(6)
	v_mov_b32_e32 v41, v25
	v_mov_b32_e32 v44, v31
	v_mov_b32_e32 v45, v27
	v_mov_b32_e32 v38, v28
	v_mov_b32_e32 v39, v24
	v_mov_b32_e32 v42, v30
	v_mov_b32_e32 v43, v26
	s_waitcnt vmcnt(5)
	v_pk_mul_f32 v[46:47], v[22:23], v[22:23]
	v_pk_mul_f32 v[48:49], v[20:21], v[20:21]
	v_pk_mul_f32 v[40:41], v[40:41], v[40:41]
	v_pk_mul_f32 v[44:45], v[44:45], v[44:45]
	v_pk_mov_b32 v[54:55], v[48:49], v[46:47] op_sel:[1,0]
	v_mov_b32_e32 v49, v47
	v_pk_fma_f32 v[38:39], v[38:39], v[38:39], v[40:41]
	v_pk_fma_f32 v[40:41], v[42:43], v[42:43], v[44:45]
	s_waitcnt vmcnt(4)
	v_mul_f32_e32 v50, v17, v17
	v_mul_f32_e32 v52, v19, v19
	v_pk_add_f32 v[42:43], v[54:55], v[48:49]
	v_pk_add_f32 v[38:39], v[38:39], v[40:41]
	v_pk_fma_f32 v[46:47], v[16:17], v[16:17], v[50:51] op_sel_hi:[1,1,0]
	v_pk_fma_f32 v[50:51], v[18:19], v[18:19], v[52:53] op_sel_hi:[1,1,0]
	s_waitcnt vmcnt(3)
	v_mul_f32_e32 v55, v12, v12
	v_mul_f32_e32 v56, v13, v13
	v_pk_add_f32 v[40:41], v[42:43], v[42:43] op_sel:[0,1] op_sel_hi:[1,0]
	v_pk_add_f32 v[38:39], v[38:39], v[38:39] op_sel:[0,1] op_sel_hi:[1,0]
	v_mul_f32_e32 v47, v14, v14
	v_mul_f32_e32 v51, v15, v15
	s_waitcnt vmcnt(2)
	v_pk_mul_f32 v[44:45], v[10:11], v[10:11]
	v_pk_mul_f32 v[48:49], v[8:9], v[8:9]
	v_mov_b32_e32 v41, v56
	v_mov_b32_e32 v39, v55
	v_pk_mov_b32 v[42:43], v[48:49], v[44:45] op_sel:[1,0]
	v_mov_b32_e32 v49, v45
	v_pk_add_f32 v[46:47], v[46:47], v[50:51]
	v_pk_add_f32 v[38:39], v[38:39], v[40:41]
	s_waitcnt vmcnt(0)
	v_mul_f32_e32 v52, v5, v5
	v_mul_f32_e32 v54, v7, v7
	v_pk_add_f32 v[42:43], v[42:43], v[48:49]
	v_pk_add_f32 v[38:39], v[38:39], v[46:47]
	v_mul_f32_e32 v57, v0, v0
	v_mul_f32_e32 v58, v1, v1
	v_mul_f32_e32 v59, v2, v2
	v_mul_f32_e32 v60, v3, v3
	v_pk_fma_f32 v[44:45], v[4:5], v[4:5], v[52:53] op_sel_hi:[1,1,0]
	v_pk_fma_f32 v[52:53], v[6:7], v[6:7], v[54:55] op_sel_hi:[1,1,0]
	v_pk_add_f32 v[42:43], v[42:43], v[42:43] op_sel:[0,1] op_sel_hi:[1,0]
	v_pk_add_f32 v[38:39], v[38:39], v[38:39] op_sel:[0,1] op_sel_hi:[1,0]
	v_mov_b32_e32 v45, v59
	v_mov_b32_e32 v53, v60
	v_mov_b32_e32 v43, v58
	v_mov_b32_e32 v39, v57
	v_pk_add_f32 v[44:45], v[44:45], v[52:53]
	v_pk_add_f32 v[38:39], v[38:39], v[42:43]
	v_mov_b32_e32 v52, 0
	v_pk_add_f32 v[38:39], v[38:39], v[44:45]
	v_mov_b32_e32 v53, 0
	v_add_f32_e32 v38, v38, v39
	ds_bpermute_b32 v39, v86, v38
	v_mov_b32_e32 v50, 0
	v_mov_b32_e32 v51, 0
	v_mov_b32_e32 v56, 0
	v_mov_b32_e32 v57, 0
	s_waitcnt lgkmcnt(0)
	v_add_f32_e32 v38, v38, v39
	ds_bpermute_b32 v39, v87, v38
	v_mov_b32_e32 v54, 0
	v_mov_b32_e32 v55, 0
	v_mov_b32_e32 v60, 0
	v_mov_b32_e32 v58, 0
	s_waitcnt lgkmcnt(0)
	v_add_f32_e32 v38, v38, v39
	ds_bpermute_b32 v39, v88, v38
	v_mov_b32_e32 v59, 0
	s_waitcnt lgkmcnt(0)
	v_add_f32_e32 v46, v38, v39
	ds_bpermute_b32 v47, v89, v46
	ds_read_b128 v[38:41], v92
	ds_read_b128 v[42:45], v92 offset:8192
	s_waitcnt lgkmcnt(2)
	v_add_f32_e32 v46, v46, v47
	ds_bpermute_b32 v47, v90, v46
	s_waitcnt lgkmcnt(0)
	v_add_f32_e32 v46, v46, v47
	ds_bpermute_b32 v47, v91, v46
	s_waitcnt lgkmcnt(0)
	v_add_f32_e32 v46, v46, v47
	v_fmamk_f32 v46, v46, 0x3a000000, v158
	v_mul_f32_e32 v47, 0x4b800000, v46
	v_cmp_gt_f32_e32 vcc, s23, v46
	s_nop 1
	v_cndmask_b32_e32 v46, v46, v47, vcc
	v_rsq_f32_e32 v46, v46
	s_nop 0
	v_mul_f32_e32 v47, 0x45800000, v46
	v_cndmask_b32_e32 v66, v46, v47, vcc
	v_pk_mul_f32 v[28:29], v[28:29], v[66:67] op_sel_hi:[1,0]
	v_pk_mul_f32 v[30:31], v[30:31], v[66:67] op_sel_hi:[1,0]
	v_pk_fma_f32 v[80:81], v[38:39], v[28:29], v[42:43]
	v_pk_fma_f32 v[78:79], v[40:41], v[30:31], v[44:45]
	v_cvt_pk_bf16_f32 v42, v80, v81
	v_pk_mul_f32 v[24:25], v[24:25], v[66:67] op_sel_hi:[1,0]
	v_cvt_pk_bf16_f32 v43, v78, v79
	ds_read_b128 v[28:31], v92 offset:1024
	ds_read_b128 v[38:41], v92 offset:9216
	v_pk_mul_f32 v[26:27], v[26:27], v[66:67] op_sel_hi:[1,0]
	global_store_dwordx2 v[68:69], v[42:43], off
	v_pk_mul_f32 v[20:21], v[20:21], v[66:67] op_sel_hi:[1,0]
	v_pk_mul_f32 v[22:23], v[22:23], v[66:67] op_sel_hi:[1,0]
	s_waitcnt lgkmcnt(0)
	v_pk_fma_f32 v[72:73], v[30:31], v[26:27], v[40:41]
	v_pk_fma_f32 v[76:77], v[28:29], v[24:25], v[38:39]
	v_pk_mul_f32 v[16:17], v[16:17], v[66:67] op_sel_hi:[1,0]
	v_cvt_pk_bf16_f32 v38, v76, v77
	v_cvt_pk_bf16_f32 v39, v72, v73
	ds_read_b128 v[24:27], v92 offset:2048
	ds_read_b128 v[28:31], v92 offset:10240
	global_store_dwordx2 v[68:69], v[38:39], off offset:512
	v_pk_mul_f32 v[18:19], v[18:19], v[66:67] op_sel_hi:[1,0]
	v_pk_mul_f32 v[12:13], v[12:13], v[66:67] op_sel_hi:[1,0]
	v_pk_mul_f32 v[14:15], v[14:15], v[66:67] op_sel_hi:[1,0]
	s_waitcnt lgkmcnt(0)
; #define LAS __attribute__((address_space(3)))
; __device__ __forceinline__ unsigned cvt_pk_bf16(float lo, float hi) { unsigned r; asm volatile("v_cvt_pk_bf16_f32 %0, %1, %2" : "=v"(r) : "v"(lo), "v"(hi)); return r; }
; template <bool POST, bool PRE>
; __device__ __forceinline__ void row_core(const Params& P, const RowCfg& c, LAS float* vA, LAS float* vB, LAS float* vP, const bf16_t* RAW, const float* SSQ, bf16_t* H, int row, int lane, f32x4 (&v)[8]) {
;     const f32x4* xs = (const f32x4*)(c.xsrc + (size_t)row * DM) + lane;
; #pragma unroll
;     for (int j = 0; j < 8; ++j) v[j] = xs[64 * j];
;     if (POST) {
;         const u32x2* rs = (const u32x2*)(RAW + (size_t)row * DM) + lane;
;         float s = (lane < 32) ? SSQ[(size_t)row * 32 + lane] : 0.f; s = wave_sum(s);
;         const float rstd = rsqrtf(s * (1.0f / DM) + EPS);
;         f32x4* os = (f32x4*)(P.out + (size_t)row * DM) + lane;
; #pragma unroll
;         for (int j = 0; j < 8; ++j) { const u32x2 rb = rs[64 * j]; const f32x4 r = (f32x4){__uint_as_float(rb.x << 16), __uint_as_float(rb.x & 0xffff0000u), __uint_as_float(rb.y << 16), __uint_as_float(rb.y & 0xffff0000u)};
;             const f32x4 pv = *(const LAS f32x4*)(vP + j * 256 + lane * 4); v[j] += r * rstd * pv; os[64 * j] = v[j]; }
;     }
;     if (PRE) {
;         float s2 = 0.f;
; #pragma unroll
;         for (int j = 0; j < 8; ++j) s2 += (v[j][0] * v[j][0] + v[j][1] * v[j][1]) + (v[j][2] * v[j][2] + v[j][3] * v[j][3]);
;         s2 = wave_sum(s2);
;         const float rstd2 = rsqrtf(s2 * (1.0f / DM) + EPS);
;         u32x2* hs = (u32x2*)(H + (size_t)row * DM) + lane;
; #pragma unroll
;         for (int j = 0; j < 8; ++j) { const f32x4 a = *(const LAS f32x4*)(vA + j * 256 + lane * 4), b = *(const LAS f32x4*)(vB + j * 256 + lane * 4);
;             v[j] = v[j] * rstd2 * a + b; u32x2 w; w.x = cvt_pk_bf16(v[j][0], v[j][1]); w.y = cvt_pk_bf16(v[j][2], v[j][3]); hs[64 * j] = w; }
	v_pk_fma_f32 v[46:47], v[26:27], v[22:23], v[30:31]
	v_pk_fma_f32 v[48:49], v[24:25], v[20:21], v[28:29]
	v_pk_mul_f32 v[8:9], v[8:9], v[66:67] op_sel_hi:[1,0]
	v_cvt_pk_bf16_f32 v28, v48, v49
	v_cvt_pk_bf16_f32 v29, v46, v47
	ds_read_b128 v[20:23], v92 offset:3072
	ds_read_b128 v[24:27], v92 offset:11264
	global_store_dwordx2 v[68:69], v[28:29], off offset:1024
	v_pk_mul_f32 v[10:11], v[10:11], v[66:67] op_sel_hi:[1,0]
	v_pk_mul_f32 v[4:5], v[4:5], v[66:67] op_sel_hi:[1,0]
	v_pk_mul_f32 v[6:7], v[6:7], v[66:67] op_sel_hi:[1,0]
	s_waitcnt lgkmcnt(0)
	v_pk_fma_f32 v[42:43], v[18:19], v[22:23], v[26:27]
	v_pk_fma_f32 v[44:45], v[16:17], v[20:21], v[24:25]
	v_pk_mul_f32 v[0:1], v[0:1], v[66:67] op_sel_hi:[1,0]
	v_cvt_pk_bf16_f32 v24, v44, v45
	v_cvt_pk_bf16_f32 v25, v42, v43
	ds_read_b128 v[16:19], v92 offset:4096
	ds_read_b128 v[20:23], v92 offset:12288
	global_store_dwordx2 v[68:69], v[24:25], off offset:1536
	v_pk_mul_f32 v[2:3], v[2:3], v[66:67] op_sel_hi:[1,0]
	v_mov_b32_e32 v66, 0
	v_mov_b32_e32 v67, 0
	s_waitcnt lgkmcnt(0)
	v_pk_fma_f32 v[38:39], v[14:15], v[18:19], v[22:23]
	v_pk_fma_f32 v[40:41], v[12:13], v[16:17], v[20:21]
	v_mov_b32_e32 v16, 0
	v_cvt_pk_bf16_f32 v22, v40, v41
	v_cvt_pk_bf16_f32 v23, v38, v39
	ds_read_b128 v[12:15], v92 offset:5120
	ds_read_b128 v[18:21], v92 offset:13312
	global_store_dwordx2 v[68:69], v[22:23], off offset:2048
	v_mov_b32_e32 v17, 0
	s_waitcnt lgkmcnt(0)
	v_pk_fma_f32 v[28:29], v[10:11], v[14:15], v[20:21]
	v_pk_fma_f32 v[30:31], v[8:9], v[12:13], v[18:19]
	s_nop 0
	v_cvt_pk_bf16_f32 v18, v30, v31
	v_cvt_pk_bf16_f32 v19, v28, v29
	ds_read_b128 v[8:11], v92 offset:6144
	ds_read_b128 v[12:15], v92 offset:14336
	global_store_dwordx2 v[68:69], v[18:19], off offset:2560
	v_mov_b32_e32 v18, 0
	v_mov_b32_e32 v19, 0
	s_waitcnt lgkmcnt(0)
	v_pk_fma_f32 v[24:25], v[6:7], v[10:11], v[14:15]
	v_pk_fma_f32 v[26:27], v[4:5], v[8:9], v[12:13]
	s_nop 0
	v_cvt_pk_bf16_f32 v12, v26, v27
	v_cvt_pk_bf16_f32 v13, v24, v25
	ds_read_b128 v[4:7], v92 offset:7168
	ds_read_b128 v[8:11], v92 offset:15360
	global_store_dwordx2 v[68:69], v[12:13], off offset:3072
	s_waitcnt lgkmcnt(0)
	v_pk_fma_f32 v[20:21], v[2:3], v[6:7], v[10:11]
	v_pk_fma_f32 v[22:23], v[0:1], v[4:5], v[8:9]
	s_nop 0
	v_cvt_pk_bf16_f32 v0, v22, v23
	v_cvt_pk_bf16_f32 v1, v20, v21
	global_store_dwordx2 v[68:69], v[0:1], off offset:3584
	v_mov_b32_e32 v68, 0
	v_mov_b32_e32 v69, 0
	s_cbranch_scc1 .LBB0_186
	s_ashr_i32 s17, s16, 31
	s_lshl_b64 s[20:21], s[16:17], 13
	v_lshl_add_u64 v[0:1], v[32:33], 0, s[20:21]
	global_load_dwordx4 v[50:53], v[0:1], off nt
	global_load_dwordx4 v[54:57], v[0:1], off offset:1024 nt
	global_load_dwordx4 v[58:61], v[0:1], off offset:2048 nt
	global_load_dwordx4 v[16:19], v[0:1], off offset:3072 nt
	v_add_co_u32_e32 v0, vcc, 0x1000, v0
	s_lshl_b64 s[20:21], s[16:17], 12
	s_nop 0
	v_addc_co_u32_e32 v1, vcc, 0, v1, vcc
	global_load_dwordx4 v[12:15], v[0:1], off nt
	global_load_dwordx4 v[8:11], v[0:1], off offset:1024 nt
	global_load_dwordx4 v[4:7], v[0:1], off offset:2048 nt
	s_nop 0
	global_load_dwordx4 v[0:3], v[0:1], off offset:3072 nt
	v_lshl_add_u64 v[162:163], v[34:35], 0, s[20:21]
	s_waitcnt vmcnt(7)
	v_mov_b32_e32 v64, v51
	s_waitcnt vmcnt(6)
	v_mov_b32_e32 v65, v55
	v_mov_b32_e32 v62, v50
	v_mov_b32_e32 v63, v54
	v_pk_mul_f32 v[64:65], v[64:65], v[64:65]
	v_mov_b32_e32 v66, v53
	v_mov_b32_e32 v67, v57
	v_pk_fma_f32 v[62:63], v[62:63], v[62:63], v[64:65]
	v_mov_b32_e32 v64, v52
	v_mov_b32_e32 v65, v56
	v_pk_mul_f32 v[66:67], v[66:67], v[66:67]
	s_nop 0
	v_pk_fma_f32 v[64:65], v[64:65], v[64:65], v[66:67]
	s_waitcnt vmcnt(5)
	v_pk_mul_f32 v[66:67], v[58:59], v[58:59]
	v_pk_add_f32 v[62:63], v[62:63], v[64:65]
	v_pk_mul_f32 v[64:65], v[60:61], v[60:61]
	v_pk_add_f32 v[62:63], v[62:63], v[62:63] op_sel:[0,1] op_sel_hi:[1,0]
	v_pk_mov_b32 v[68:69], v[66:67], v[64:65] op_sel:[1,0]
	v_mov_b32_e32 v67, v65
	v_pk_add_f32 v[64:65], v[68:69], v[66:67]
	s_waitcnt vmcnt(3)
	v_mul_f32_e32 v66, v12, v12
	v_mul_f32_e32 v67, v13, v13
	v_pk_add_f32 v[64:65], v[64:65], v[64:65] op_sel:[0,1] op_sel_hi:[1,0]
	v_mov_b32_e32 v63, v66
	v_mov_b32_e32 v65, v67
	v_pk_add_f32 v[62:63], v[62:63], v[64:65]
	v_mul_f32_e32 v64, v17, v17
	v_mul_f32_e32 v66, v19, v19
	v_mul_f32_e32 v68, v14, v14
	v_mul_f32_e32 v69, v15, v15
	v_pk_fma_f32 v[64:65], v[16:17], v[16:17], v[64:65] op_sel_hi:[1,1,0]
	v_pk_fma_f32 v[66:67], v[18:19], v[18:19], v[66:67] op_sel_hi:[1,1,0]
	v_mov_b32_e32 v65, v68
	v_mov_b32_e32 v67, v69
	v_pk_add_f32 v[64:65], v[64:65], v[66:67]
	s_waitcnt vmcnt(2)
	v_pk_mul_f32 v[66:67], v[8:9], v[8:9]
	v_pk_add_f32 v[62:63], v[62:63], v[64:65]
	v_pk_mul_f32 v[64:65], v[10:11], v[10:11]
	v_pk_add_f32 v[62:63], v[62:63], v[62:63] op_sel:[0,1] op_sel_hi:[1,0]
	v_pk_mov_b32 v[68:69], v[66:67], v[64:65] op_sel:[1,0]
	v_mov_b32_e32 v67, v65
	v_pk_add_f32 v[64:65], v[68:69], v[66:67]
	s_waitcnt vmcnt(0)
; #define LAS __attribute__((address_space(3)))
; __device__ __forceinline__ unsigned cvt_pk_bf16(float lo, float hi) { unsigned r; asm volatile("v_cvt_pk_bf16_f32 %0, %1, %2" : "=v"(r) : "v"(lo), "v"(hi)); return r; }
; __device__ __forceinline__ float wave_sum(float v) {
; #pragma unroll
;     for (int o = 1; o < 64; o <<= 1) v += __shfl_xor(v, o);
;     return v;
; template <bool POST, bool PRE>
; __device__ __forceinline__ void row_core(const Params& P, const RowCfg& c, LAS float* vA, LAS float* vB, LAS float* vP, const bf16_t* RAW, const float* SSQ, bf16_t* H, int row, int lane, f32x4 (&v)[8]) {
;     ...
;         float s2 = 0.f;
; #pragma unroll
;         for (int j = 0; j < 8; ++j) s2 += (v[j][0] * v[j][0] + v[j][1] * v[j][1]) + (v[j][2] * v[j][2] + v[j][3] * v[j][3]);
;         s2 = wave_sum(s2);
;         const float rstd2 = rsqrtf(s2 * (1.0f / DM) + EPS);
;         u32x2* hs = (u32x2*)(H + (size_t)row * DM) + lane;
; #pragma unroll
;         for (int j = 0; j < 8; ++j) { const f32x4 a = *(const LAS f32x4*)(vA + j * 256 + lane * 4), b = *(const LAS f32x4*)(vB + j * 256 + lane * 4);
;             v[j] = v[j] * rstd2 * a + b; u32x2 w; w.x = cvt_pk_bf16(v[j][0], v[j][1]); w.y = cvt_pk_bf16(v[j][2], v[j][3]); hs[64 * j] = w; }
	v_mul_f32_e32 v66, v0, v0
	v_mul_f32_e32 v67, v1, v1
	v_pk_add_f32 v[64:65], v[64:65], v[64:65] op_sel:[0,1] op_sel_hi:[1,0]
	v_mov_b32_e32 v63, v66
	v_mov_b32_e32 v65, v67
	v_pk_add_f32 v[62:63], v[62:63], v[64:65]
	v_mul_f32_e32 v64, v5, v5
	v_mul_f32_e32 v66, v7, v7
	v_mul_f32_e32 v68, v2, v2
	v_mul_f32_e32 v69, v3, v3
	v_pk_fma_f32 v[64:65], v[4:5], v[4:5], v[64:65] op_sel_hi:[1,1,0]
	v_pk_fma_f32 v[66:67], v[6:7], v[6:7], v[66:67] op_sel_hi:[1,1,0]
	v_mov_b32_e32 v65, v68
	v_mov_b32_e32 v67, v69
	v_pk_add_f32 v[64:65], v[64:65], v[66:67]
	s_nop 0
	v_pk_add_f32 v[62:63], v[62:63], v[64:65]
	s_nop 0
	v_add_f32_e32 v62, v62, v63
	s_nop 1
	v_add_f32_dpp v62, v62, v62 quad_perm:[1,0,3,2] row_mask:0xf bank_mask:0xf
	s_nop 1
	v_add_f32_dpp v62, v62, v62 quad_perm:[2,3,0,1] row_mask:0xf bank_mask:0xf
	s_nop 1
	v_add_f32_dpp v62, v62, v62 row_half_mirror row_mask:0xf bank_mask:0xf
	s_nop 1
	v_add_f32_dpp v62, v62, v62 row_mirror row_mask:0xf bank_mask:0xf
	ds_bpermute_b32 v63, v90, v62
	s_waitcnt lgkmcnt(0)
	v_add_f32_e32 v62, v62, v63
	ds_bpermute_b32 v63, v91, v62
	s_waitcnt lgkmcnt(0)
	v_add_f32_e32 v62, v62, v63
	v_fmamk_f32 v62, v62, 0x3a000000, v158
	v_cmp_gt_f32_e32 vcc, s23, v62
	v_mul_f32_e32 v63, 0x4b800000, v62
	s_nop 0
	v_cndmask_b32_e32 v62, v62, v63, vcc
	v_rsq_f32_e32 v62, v62
	s_nop 0
	v_mul_f32_e32 v63, 0x45800000, v62
	v_cndmask_b32_e32 v160, v62, v63, vcc
	ds_read_b128 v[62:65], v92
	ds_read_b128 v[66:69], v92 offset:8192
	v_pk_mul_f32 v[50:51], v[50:51], v[160:161] op_sel_hi:[1,0]
	v_pk_mul_f32 v[52:53], v[52:53], v[160:161] op_sel_hi:[1,0]
	v_pk_mul_f32 v[54:55], v[54:55], v[160:161] op_sel_hi:[1,0]
	v_pk_mul_f32 v[56:57], v[56:57], v[160:161] op_sel_hi:[1,0]
	s_waitcnt lgkmcnt(0)
	v_pk_fma_f32 v[82:83], v[64:65], v[52:53], v[68:69]
	v_pk_fma_f32 v[84:85], v[62:63], v[50:51], v[66:67]
	v_pk_mul_f32 v[58:59], v[58:59], v[160:161] op_sel_hi:[1,0]
	v_cvt_pk_bf16_f32 v50, v84, v85
	v_cvt_pk_bf16_f32 v51, v82, v83
	global_store_dwordx2 v[162:163], v[50:51], off
	ds_read_b128 v[50:53], v92 offset:1024
	ds_read_b128 v[62:65], v92 offset:9216
	v_pk_mul_f32 v[60:61], v[60:61], v[160:161] op_sel_hi:[1,0]
	v_pk_mul_f32 v[16:17], v[16:17], v[160:161] op_sel_hi:[1,0]
	v_pk_mul_f32 v[18:19], v[18:19], v[160:161] op_sel_hi:[1,0]
	v_pk_mul_f32 v[12:13], v[12:13], v[160:161] op_sel_hi:[1,0]
	s_waitcnt lgkmcnt(0)
	v_pk_fma_f32 v[70:71], v[52:53], v[56:57], v[64:65]
	v_pk_fma_f32 v[74:75], v[50:51], v[54:55], v[62:63]
	v_pk_mul_f32 v[14:15], v[14:15], v[160:161] op_sel_hi:[1,0]
	v_cvt_pk_bf16_f32 v50, v74, v75
	v_cvt_pk_bf16_f32 v51, v70, v71
	global_store_dwordx2 v[162:163], v[50:51], off offset:512
	ds_read_b128 v[50:53], v92 offset:2048
	ds_read_b128 v[54:57], v92 offset:10240
	v_pk_mul_f32 v[8:9], v[8:9], v[160:161] op_sel_hi:[1,0]
	v_pk_mul_f32 v[10:11], v[10:11], v[160:161] op_sel_hi:[1,0]
	v_pk_mul_f32 v[4:5], v[4:5], v[160:161] op_sel_hi:[1,0]
	v_pk_mul_f32 v[6:7], v[6:7], v[160:161] op_sel_hi:[1,0]
	s_waitcnt lgkmcnt(0)
	v_pk_fma_f32 v[66:67], v[52:53], v[60:61], v[56:57]
	v_pk_fma_f32 v[68:69], v[50:51], v[58:59], v[54:55]
	v_pk_mul_f32 v[0:1], v[0:1], v[160:161] op_sel_hi:[1,0]
	v_cvt_pk_bf16_f32 v50, v68, v69
	v_cvt_pk_bf16_f32 v51, v66, v67
	global_store_dwordx2 v[162:163], v[50:51], off offset:1024
	ds_read_b128 v[50:53], v92 offset:3072
	ds_read_b128 v[54:57], v92 offset:11264
	v_pk_mul_f32 v[2:3], v[2:3], v[160:161] op_sel_hi:[1,0]
	s_waitcnt lgkmcnt(0)
	v_pk_fma_f32 v[18:19], v[18:19], v[52:53], v[56:57]
	v_pk_fma_f32 v[16:17], v[16:17], v[50:51], v[54:55]
	s_nop 0
	v_cvt_pk_bf16_f32 v50, v16, v17
	v_cvt_pk_bf16_f32 v51, v18, v19
	global_store_dwordx2 v[162:163], v[50:51], off offset:1536
	ds_read_b128 v[50:53], v92 offset:4096
	ds_read_b128 v[54:57], v92 offset:12288
	s_waitcnt lgkmcnt(0)
	v_pk_fma_f32 v[64:65], v[14:15], v[52:53], v[56:57]
	v_pk_fma_f32 v[62:63], v[12:13], v[50:51], v[54:55]
	s_nop 0
	v_cvt_pk_bf16_f32 v12, v62, v63
	v_cvt_pk_bf16_f32 v13, v64, v65
	global_store_dwordx2 v[162:163], v[12:13], off offset:2048
	ds_read_b128 v[12:15], v92 offset:5120
	ds_read_b128 v[50:53], v92 offset:13312
	s_waitcnt lgkmcnt(0)
	v_pk_fma_f32 v[58:59], v[10:11], v[14:15], v[52:53]
	v_pk_fma_f32 v[60:61], v[8:9], v[12:13], v[50:51]
	s_nop 0
	v_cvt_pk_bf16_f32 v8, v60, v61
	v_cvt_pk_bf16_f32 v9, v58, v59
	global_store_dwordx2 v[162:163], v[8:9], off offset:2560
	ds_read_b128 v[8:11], v92 offset:6144
	ds_read_b128 v[12:15], v92 offset:14336
	s_waitcnt lgkmcnt(0)
	v_pk_fma_f32 v[54:55], v[6:7], v[10:11], v[14:15]
	v_pk_fma_f32 v[56:57], v[4:5], v[8:9], v[12:13]
	s_nop 0
	v_cvt_pk_bf16_f32 v4, v56, v57
	v_cvt_pk_bf16_f32 v5, v54, v55
	global_store_dwordx2 v[162:163], v[4:5], off offset:3072
	ds_read_b128 v[4:7], v92 offset:7168
	ds_read_b128 v[8:11], v92 offset:15360
	s_waitcnt lgkmcnt(0)
	v_pk_fma_f32 v[50:51], v[2:3], v[6:7], v[10:11]
	v_pk_fma_f32 v[52:53], v[0:1], v[4:5], v[8:9]
	s_nop 0
	v_cvt_pk_bf16_f32 v0, v52, v53
	v_cvt_pk_bf16_f32 v1, v50, v51
	global_store_dwordx2 v[162:163], v[0:1], off offset:3584

; #define LAS __attribute__((address_space(3)))
; __device__ __forceinline__ unsigned pk2(float lo, float hi) { return f2bf(lo) | (f2bf(hi) << 16); }
; __device__ __forceinline__ f32x4 mfma16(bf16x8 a, bf16x8 b, f32x4 c) { return __builtin_amdgcn_mfma_f32_16x16x32_bf16(a, b, c, 0, 0, 0); }
; __device__ __forceinline__ void gdn_scan_wg(const Ctx& F, int hv, int sl) {
;     ...
;             bf16x8 sf[4];
; #pragma unroll
;             for (int ks = 0; ks < 4; ++ks) sf[ks] = *(const LAS bf16x8*)(Sb + cur * 2176 + fr * 136 + ks * 32 + fq * 8);
;             f32x4 pacc = (f32x4){0.f, 0.f, 0.f, 0.f};
; #pragma unroll
;             for (int ks = 0; ks < 4; ++ks) pacc = mfma16(x.pf[ks], sf[ks], pacc);
;             if (w < 4) {
;                 f32x4 oacc = (f32x4){__uint_as_float(x.ou.x << 16), __uint_as_float(x.ou.x & 0xffff0000u), __uint_as_float(x.ou.y << 16), __uint_as_float(x.ou.y & 0xffff0000u)};
; #pragma unroll
;                 for (int ks = 0; ks < 4; ++ks) oacc = mfma16(sf[ks], x.qf[ks], oacc);
;                 { u32x2 ob; ob.x = pk2(oacc[0], oacc[1]); ob.y = pk2(oacc[2], oacc[3]); *(u32x2*)(O + ((size_t)(hv * 8 + (dv0 >> 4)) * SEQ + (n * 64 + w * 16 + fr)) * 16 + fq * 4) = ob; }
.LBB0_954:
	s_or_b64 exec, exec, s[22:23]
	v_add_u32_e32 v241, v213, v215
	ds_read_b128 v[128:131], v241
	ds_read_b128 v[132:135], v241 offset:64
	s_and_b64 vcc, exec, s[0:1]
	s_waitcnt vmcnt(0) lgkmcnt(0)
	v_mfma_f32_16x16x32_bf16 v[72:75], v[72:75], v[128:131], 0
	v_mfma_f32_16x16x32_bf16 v[140:143], v[76:79], v[132:135], v[72:75]
	s_nop 6
	ds_read_b128 v[72:75], v241 offset:128
	ds_read_b128 v[76:79], v241 offset:192
	s_waitcnt lgkmcnt(1)
	v_mfma_f32_16x16x32_bf16 v[68:71], v[68:71], v[72:75], v[140:143]
	s_waitcnt lgkmcnt(0)
	v_mfma_f32_16x16x32_bf16 v[64:67], v[64:67], v[76:79], v[68:71]
	s_cbranch_vccnz .LBB0_956
	s_nop 4
	v_lshlrev_b32_e32 v68, 16, v156
	v_and_b32_e32 v69, 0xffff0000, v156
	v_lshlrev_b32_e32 v70, 16, v157
	v_and_b32_e32 v71, 0xffff0000, v157
	s_nop 1
	v_mfma_f32_16x16x32_bf16 v[68:71], v[128:131], v[0:3], v[68:71]
	v_mfma_f32_16x16x32_bf16 v[68:71], v[132:135], v[4:7], v[68:71]
	v_mfma_f32_16x16x32_bf16 v[68:71], v[72:75], v[8:11], v[68:71]
	v_mfma_f32_16x16x32_bf16 v[68:71], v[76:79], v[12:15], v[68:71]
	s_nop 7
	v_bfe_u32 v72, v68, 16, 1
	v_bfe_u32 v74, v70, 16, 1
	v_bfe_u32 v73, v69, 16, 1
	v_bfe_u32 v75, v71, 16, 1
	v_add3_u32 v68, v68, v72, s29
	v_add3_u32 v70, v70, v74, s29
	v_add3_u32 v69, v69, v73, s29
	v_add3_u32 v71, v71, v75, s29
	v_lshrrev_b32_e32 v68, 16, v68
	v_lshrrev_b32_e32 v70, 16, v70
	v_and_or_b32 v68, v69, s28, v68
	v_and_or_b32 v69, v71, s28, v70
	v_lshl_add_u64 v[70:71], s[92:93], 0, v[166:167]
	global_store_dwordx2 v[70:71], v[68:69], off nt

; #define LAS __attribute__((address_space(3)))
; __device__ __forceinline__ unsigned pk2(float lo, float hi) { return f2bf(lo) | (f2bf(hi) << 16); }
; __device__ __forceinline__ f32x4 mfma16(bf16x8 a, bf16x8 b, f32x4 c) { return __builtin_amdgcn_mfma_f32_16x16x32_bf16(a, b, c, 0, 0, 0); }
; __device__ __forceinline__ void gdn_scan_wg(const Ctx& F, int hv, int sl) {
;     ...
;             bf16x8 sf[4];
; #pragma unroll
;             for (int ks = 0; ks < 4; ++ks) sf[ks] = *(const LAS bf16x8*)(Sb + cur * 2176 + fr * 136 + ks * 32 + fq * 8);
;             f32x4 pacc = (f32x4){0.f, 0.f, 0.f, 0.f};
; #pragma unroll
;             for (int ks = 0; ks < 4; ++ks) pacc = mfma16(x.pf[ks], sf[ks], pacc);
;             if (w < 4) {
;                 f32x4 oacc = (f32x4){__uint_as_float(x.ou.x << 16), __uint_as_float(x.ou.x & 0xffff0000u), __uint_as_float(x.ou.y << 16), __uint_as_float(x.ou.y & 0xffff0000u)};
; #pragma unroll
;                 for (int ks = 0; ks < 4; ++ks) oacc = mfma16(sf[ks], x.qf[ks], oacc);
;                 { u32x2 ob; ob.x = pk2(oacc[0], oacc[1]); ob.y = pk2(oacc[2], oacc[3]); *(u32x2*)(O + ((size_t)(hv * 8 + (dv0 >> 4)) * SEQ + (n * 64 + w * 16 + fr)) * 16 + fq * 4) = ob; }
.LBB0_960:
	s_or_b64 exec, exec, s[22:23]
	ds_read_b128 v[72:75], v241 offset:4352
	ds_read_b128 v[76:79], v241 offset:4416
	s_and_b64 vcc, exec, s[0:1]
	s_waitcnt lgkmcnt(1)
	v_mfma_f32_16x16x32_bf16 v[68:71], v[88:91], v[72:75], 0
	s_waitcnt lgkmcnt(0)
	v_mfma_f32_16x16x32_bf16 v[68:71], v[92:95], v[76:79], v[68:71]
	ds_read_b128 v[88:91], v241 offset:4480
	ds_read_b128 v[92:95], v241 offset:4544
	s_waitcnt lgkmcnt(1)
	v_mfma_f32_16x16x32_bf16 v[68:71], v[84:87], v[88:91], v[68:71]
	s_waitcnt lgkmcnt(0)
	v_mfma_f32_16x16x32_bf16 v[68:71], v[80:83], v[92:95], v[68:71]
	s_cbranch_vccnz .LBB0_962
	v_lshlrev_b32_e32 v80, 16, v158
	v_and_b32_e32 v81, 0xffff0000, v158
	v_lshlrev_b32_e32 v82, 16, v159
	v_and_b32_e32 v83, 0xffff0000, v159
	s_nop 1
	v_mfma_f32_16x16x32_bf16 v[72:75], v[72:75], v[16:19], v[80:83]
	v_mfma_f32_16x16x32_bf16 v[72:75], v[76:79], v[20:23], v[72:75]
	v_mfma_f32_16x16x32_bf16 v[72:75], v[88:91], v[24:27], v[72:75]
	v_mfma_f32_16x16x32_bf16 v[72:75], v[92:95], v[28:31], v[72:75]
	s_nop 7
	v_bfe_u32 v76, v72, 16, 1
	v_bfe_u32 v78, v74, 16, 1
	v_bfe_u32 v77, v73, 16, 1
	v_bfe_u32 v79, v75, 16, 1
	v_add3_u32 v72, v72, v76, s29
	v_add3_u32 v74, v74, v78, s29
	v_add3_u32 v73, v73, v77, s29
	v_add3_u32 v75, v75, v79, s29
	v_lshrrev_b32_e32 v72, 16, v72
	v_lshrrev_b32_e32 v74, 16, v74
	v_and_or_b32 v72, v73, s28, v72
	v_and_or_b32 v73, v75, s28, v74
	v_lshl_add_u64 v[74:75], s[92:93], 0, v[206:207]
	global_store_dwordx2 v[74:75], v[72:73], off nt

; #define LAS __attribute__((address_space(3)))
; __device__ __forceinline__ unsigned pk2(float lo, float hi) { return f2bf(lo) | (f2bf(hi) << 16); }
; __device__ __forceinline__ f32x4 mfma16(bf16x8 a, bf16x8 b, f32x4 c) { return __builtin_amdgcn_mfma_f32_16x16x32_bf16(a, b, c, 0, 0, 0); }
; __device__ __forceinline__ void gdn_scan_wg(const Ctx& F, int hv, int sl) {
;     ...
;             bf16x8 sf[4];
; #pragma unroll
;             for (int ks = 0; ks < 4; ++ks) sf[ks] = *(const LAS bf16x8*)(Sb + cur * 2176 + fr * 136 + ks * 32 + fq * 8);
;             f32x4 pacc = (f32x4){0.f, 0.f, 0.f, 0.f};
; #pragma unroll
;             for (int ks = 0; ks < 4; ++ks) pacc = mfma16(x.pf[ks], sf[ks], pacc);
;             if (w < 4) {
;                 f32x4 oacc = (f32x4){__uint_as_float(x.ou.x << 16), __uint_as_float(x.ou.x & 0xffff0000u), __uint_as_float(x.ou.y << 16), __uint_as_float(x.ou.y & 0xffff0000u)};
; #pragma unroll
;                 for (int ks = 0; ks < 4; ++ks) oacc = mfma16(sf[ks], x.qf[ks], oacc);
;                 { u32x2 ob; ob.x = pk2(oacc[0], oacc[1]); ob.y = pk2(oacc[2], oacc[3]); *(u32x2*)(O + ((size_t)(hv * 8 + (dv0 >> 4)) * SEQ + (n * 64 + w * 16 + fr)) * 16 + fq * 4) = ob; }
.LBB0_966:
	s_or_b64 exec, exec, s[22:23]
	ds_read_b128 v[76:79], v241
	ds_read_b128 v[84:87], v241 offset:64
	ds_read_b128 v[88:91], v241 offset:128
	ds_read_b128 v[92:95], v241 offset:192
	s_and_b64 vcc, exec, s[0:1]
	s_waitcnt lgkmcnt(3)
	v_mfma_f32_16x16x32_bf16 v[72:75], v[104:107], v[76:79], 0
	s_waitcnt lgkmcnt(2)
	v_mfma_f32_16x16x32_bf16 v[72:75], v[108:111], v[84:87], v[72:75]
	s_waitcnt lgkmcnt(1)
	v_mfma_f32_16x16x32_bf16 v[72:75], v[100:103], v[88:91], v[72:75]
	s_waitcnt lgkmcnt(0)
	v_mfma_f32_16x16x32_bf16 v[72:75], v[96:99], v[92:95], v[72:75]
	s_cbranch_vccnz .LBB0_968
	v_lshlrev_b32_e32 v96, 16, v168
	v_and_b32_e32 v97, 0xffff0000, v168
	v_lshlrev_b32_e32 v98, 16, v169
	v_and_b32_e32 v99, 0xffff0000, v169
	s_nop 1
	v_mfma_f32_16x16x32_bf16 v[76:79], v[76:79], v[32:35], v[96:99]
	v_mfma_f32_16x16x32_bf16 v[76:79], v[84:87], v[36:39], v[76:79]
	v_mfma_f32_16x16x32_bf16 v[76:79], v[88:91], v[40:43], v[76:79]
	v_mfma_f32_16x16x32_bf16 v[76:79], v[92:95], v[44:47], v[76:79]
	s_nop 7
	v_bfe_u32 v84, v76, 16, 1
	v_bfe_u32 v86, v78, 16, 1
	v_bfe_u32 v85, v77, 16, 1
	v_bfe_u32 v87, v79, 16, 1
	v_add3_u32 v76, v76, v84, s29
	v_add3_u32 v78, v78, v86, s29
	v_add3_u32 v77, v77, v85, s29
	v_add3_u32 v79, v79, v87, s29
	v_lshrrev_b32_e32 v76, 16, v76
	v_lshrrev_b32_e32 v78, 16, v78
	v_and_or_b32 v76, v77, s28, v76
	v_and_or_b32 v77, v79, s28, v78
	v_lshl_add_u64 v[78:79], s[92:93], 0, v[204:205]
	global_store_dwordx2 v[78:79], v[76:77], off nt

; #define LAS __attribute__((address_space(3)))
; __device__ __forceinline__ unsigned pk2(float lo, float hi) { return f2bf(lo) | (f2bf(hi) << 16); }
; __device__ __forceinline__ f32x4 mfma16(bf16x8 a, bf16x8 b, f32x4 c) { return __builtin_amdgcn_mfma_f32_16x16x32_bf16(a, b, c, 0, 0, 0); }
; __device__ __forceinline__ void gdn_scan_wg(const Ctx& F, int hv, int sl) {
;     ...
;             bf16x8 sf[4];
; #pragma unroll
;             for (int ks = 0; ks < 4; ++ks) sf[ks] = *(const LAS bf16x8*)(Sb + cur * 2176 + fr * 136 + ks * 32 + fq * 8);
;             f32x4 pacc = (f32x4){0.f, 0.f, 0.f, 0.f};
; #pragma unroll
;             for (int ks = 0; ks < 4; ++ks) pacc = mfma16(x.pf[ks], sf[ks], pacc);
;             if (w < 4) {
;                 f32x4 oacc = (f32x4){__uint_as_float(x.ou.x << 16), __uint_as_float(x.ou.x & 0xffff0000u), __uint_as_float(x.ou.y << 16), __uint_as_float(x.ou.y & 0xffff0000u)};
; #pragma unroll
;                 for (int ks = 0; ks < 4; ++ks) oacc = mfma16(sf[ks], x.qf[ks], oacc);
;                 { u32x2 ob; ob.x = pk2(oacc[0], oacc[1]); ob.y = pk2(oacc[2], oacc[3]); *(u32x2*)(O + ((size_t)(hv * 8 + (dv0 >> 4)) * SEQ + (n * 64 + w * 16 + fr)) * 16 + fq * 4) = ob; }
.LBB0_972:
	s_or_b64 exec, exec, s[22:23]
	ds_read_b128 v[88:91], v241 offset:4352
	ds_read_b128 v[92:95], v241 offset:4416
	ds_read_b128 v[100:103], v241 offset:4480
	ds_read_b128 v[104:107], v241 offset:4544
	s_and_b64 vcc, exec, s[0:1]
	s_waitcnt lgkmcnt(3)
	v_mfma_f32_16x16x32_bf16 v[76:79], v[120:123], v[88:91], 0
	s_waitcnt lgkmcnt(2)
	v_mfma_f32_16x16x32_bf16 v[76:79], v[124:127], v[92:95], v[76:79]
	s_waitcnt lgkmcnt(1)
	v_mfma_f32_16x16x32_bf16 v[76:79], v[116:119], v[100:103], v[76:79]
	s_waitcnt lgkmcnt(0)
	v_mfma_f32_16x16x32_bf16 v[76:79], v[112:115], v[104:107], v[76:79]
	s_cbranch_vccnz .LBB0_974
	v_lshlrev_b32_e32 v112, 16, v208
	v_and_b32_e32 v113, 0xffff0000, v208
	v_lshlrev_b32_e32 v114, 16, v209
	v_and_b32_e32 v115, 0xffff0000, v209
	s_nop 1
	v_mfma_f32_16x16x32_bf16 v[88:91], v[88:91], v[48:51], v[112:115]
	v_mfma_f32_16x16x32_bf16 v[88:91], v[92:95], v[52:55], v[88:91]
	v_mfma_f32_16x16x32_bf16 v[88:91], v[100:103], v[56:59], v[88:91]
	v_mfma_f32_16x16x32_bf16 v[88:91], v[104:107], v[60:63], v[88:91]
	s_nop 7
	v_bfe_u32 v92, v88, 16, 1
	v_bfe_u32 v94, v90, 16, 1
	v_bfe_u32 v93, v89, 16, 1
	v_bfe_u32 v95, v91, 16, 1
	v_add3_u32 v88, v88, v92, s29
	v_add3_u32 v90, v90, v94, s29
	v_add3_u32 v89, v89, v93, s29
	v_add3_u32 v91, v91, v95, s29
	v_lshrrev_b32_e32 v88, 16, v88
	v_lshrrev_b32_e32 v90, 16, v90
	v_and_or_b32 v88, v89, s28, v88
	v_and_or_b32 v89, v91, s28, v90
	v_lshl_add_u64 v[90:91], s[92:93], 0, v[202:203]
	global_store_dwordx2 v[90:91], v[88:89], off nt

; #define LAS __attribute__((address_space(3)))
; __device__ __forceinline__ unsigned pk2(float lo, float hi) { return f2bf(lo) | (f2bf(hi) << 16); }
; __device__ __forceinline__ f32x4 mfma16(bf16x8 a, bf16x8 b, f32x4 c) { return __builtin_amdgcn_mfma_f32_16x16x32_bf16(a, b, c, 0, 0, 0); }
; __device__ __forceinline__ void gdn_scan_wg(const Ctx& F, int hv, int sl) {
;     ...
;             bf16x8 sf[4];
; #pragma unroll
;             for (int ks = 0; ks < 4; ++ks) sf[ks] = *(const LAS bf16x8*)(Sb + cur * 2176 + fr * 136 + ks * 32 + fq * 8);
;             f32x4 pacc = (f32x4){0.f, 0.f, 0.f, 0.f};
; #pragma unroll
;             for (int ks = 0; ks < 4; ++ks) pacc = mfma16(x.pf[ks], sf[ks], pacc);
;             if (w < 4) {
;                 f32x4 oacc = (f32x4){__uint_as_float(x.ou.x << 16), __uint_as_float(x.ou.x & 0xffff0000u), __uint_as_float(x.ou.y << 16), __uint_as_float(x.ou.y & 0xffff0000u)};
; #pragma unroll
;                 for (int ks = 0; ks < 4; ++ks) oacc = mfma16(sf[ks], x.qf[ks], oacc);
;                 { u32x2 ob; ob.x = pk2(oacc[0], oacc[1]); ob.y = pk2(oacc[2], oacc[3]); *(u32x2*)(O + ((size_t)(hv * 8 + (dv0 >> 4)) * SEQ + (n * 64 + w * 16 + fr)) * 16 + fq * 4) = ob; }
.LBB0_978:
	s_or_b64 exec, exec, s[22:23]
	ds_read_b128 v[92:95], v241
	ds_read_b128 v[104:107], v241 offset:64
	s_and_b64 vcc, exec, s[0:1]
	s_waitcnt vmcnt(19) lgkmcnt(1)
	v_mfma_f32_16x16x32_bf16 v[108:111], v[140:143], v[92:95], 0
	s_waitcnt lgkmcnt(0)
	v_mfma_f32_16x16x32_bf16 v[124:127], v[128:131], v[104:107], v[108:111]
	s_nop 5
	ds_read_b128 v[108:111], v241 offset:128
	ds_read_b128 v[116:119], v241 offset:192
	s_waitcnt lgkmcnt(1)
	v_mfma_f32_16x16x32_bf16 v[64:67], v[64:67], v[108:111], v[124:127]
	s_waitcnt lgkmcnt(0)
	v_mfma_f32_16x16x32_bf16 v[64:67], v[132:135], v[116:119], v[64:67]
	s_cbranch_vccnz .LBB0_980
	s_waitcnt vmcnt(18)
	v_lshlrev_b32_e32 v124, 16, v156
	v_and_b32_e32 v125, 0xffff0000, v156
	v_lshlrev_b32_e32 v126, 16, v157
	v_and_b32_e32 v127, 0xffff0000, v157
	s_nop 1
	v_mfma_f32_16x16x32_bf16 v[92:95], v[92:95], v[0:3], v[124:127]
	v_mfma_f32_16x16x32_bf16 v[92:95], v[104:107], v[4:7], v[92:95]
	v_mfma_f32_16x16x32_bf16 v[92:95], v[108:111], v[8:11], v[92:95]
	v_mfma_f32_16x16x32_bf16 v[92:95], v[116:119], v[12:15], v[92:95]
	s_nop 7
	v_bfe_u32 v104, v92, 16, 1
	v_bfe_u32 v106, v94, 16, 1
	v_bfe_u32 v105, v93, 16, 1
	v_bfe_u32 v107, v95, 16, 1
	v_add3_u32 v92, v92, v104, s29
	v_add3_u32 v94, v94, v106, s29
	v_add3_u32 v93, v93, v105, s29
	v_add3_u32 v95, v95, v107, s29
	v_lshrrev_b32_e32 v92, 16, v92
	v_lshrrev_b32_e32 v94, 16, v94
	v_and_or_b32 v92, v93, s28, v92
	v_and_or_b32 v93, v95, s28, v94
	v_lshl_add_u64 v[94:95], s[92:93], 0, v[200:201]
	global_store_dwordx2 v[94:95], v[92:93], off nt

; #define LAS __attribute__((address_space(3)))
; __device__ __forceinline__ unsigned pk2(float lo, float hi) { return f2bf(lo) | (f2bf(hi) << 16); }
; __device__ __forceinline__ f32x4 mfma16(bf16x8 a, bf16x8 b, f32x4 c) { return __builtin_amdgcn_mfma_f32_16x16x32_bf16(a, b, c, 0, 0, 0); }
; __device__ __forceinline__ void gdn_scan_wg(const Ctx& F, int hv, int sl) {
;     ...
;             bf16x8 sf[4];
; #pragma unroll
;             for (int ks = 0; ks < 4; ++ks) sf[ks] = *(const LAS bf16x8*)(Sb + cur * 2176 + fr * 136 + ks * 32 + fq * 8);
;             f32x4 pacc = (f32x4){0.f, 0.f, 0.f, 0.f};
; #pragma unroll
;             for (int ks = 0; ks < 4; ++ks) pacc = mfma16(x.pf[ks], sf[ks], pacc);
;             if (w < 4) {
;                 f32x4 oacc = (f32x4){__uint_as_float(x.ou.x << 16), __uint_as_float(x.ou.x & 0xffff0000u), __uint_as_float(x.ou.y << 16), __uint_as_float(x.ou.y & 0xffff0000u)};
; #pragma unroll
;                 for (int ks = 0; ks < 4; ++ks) oacc = mfma16(sf[ks], x.qf[ks], oacc);
;                 { u32x2 ob; ob.x = pk2(oacc[0], oacc[1]); ob.y = pk2(oacc[2], oacc[3]); *(u32x2*)(O + ((size_t)(hv * 8 + (dv0 >> 4)) * SEQ + (n * 64 + w * 16 + fr)) * 16 + fq * 4) = ob; }
.LBB0_984:
	s_or_b64 exec, exec, s[22:23]
	ds_read_b128 v[108:111], v241 offset:4352
	ds_read_b128 v[120:123], v241 offset:4416
	s_and_b64 vcc, exec, s[0:1]
	s_waitcnt vmcnt(19) lgkmcnt(1)
	v_mfma_f32_16x16x32_bf16 v[124:127], v[144:147], v[108:111], 0
	s_waitcnt lgkmcnt(0)
	v_mfma_f32_16x16x32_bf16 v[132:135], v[80:83], v[120:123], v[124:127]
	ds_read_b128 v[80:83], v241 offset:4480
	s_nop 4
	ds_read_b128 v[124:127], v241 offset:4544
	s_waitcnt lgkmcnt(1)
	v_mfma_f32_16x16x32_bf16 v[68:71], v[68:71], v[80:83], v[132:135]
	s_waitcnt lgkmcnt(0)
	v_mfma_f32_16x16x32_bf16 v[68:71], v[136:139], v[124:127], v[68:71]
	s_cbranch_vccnz .LBB0_986
	s_waitcnt vmcnt(18)
	v_lshlrev_b32_e32 v132, 16, v158
	v_and_b32_e32 v133, 0xffff0000, v158
	v_lshlrev_b32_e32 v134, 16, v159
	v_and_b32_e32 v135, 0xffff0000, v159
	s_nop 1
	v_mfma_f32_16x16x32_bf16 v[108:111], v[108:111], v[16:19], v[132:135]
	v_mfma_f32_16x16x32_bf16 v[108:111], v[120:123], v[20:23], v[108:111]
	v_mfma_f32_16x16x32_bf16 v[80:83], v[80:83], v[24:27], v[108:111]
	v_mfma_f32_16x16x32_bf16 v[80:83], v[124:127], v[28:31], v[80:83]
	s_nop 7
	v_bfe_u32 v108, v80, 16, 1
	v_bfe_u32 v110, v82, 16, 1
	v_bfe_u32 v109, v81, 16, 1
	v_bfe_u32 v111, v83, 16, 1
	v_add3_u32 v80, v80, v108, s29
	v_add3_u32 v82, v82, v110, s29
	v_add3_u32 v81, v81, v109, s29
	v_add3_u32 v83, v83, v111, s29
	v_lshrrev_b32_e32 v80, 16, v80
	v_lshrrev_b32_e32 v82, 16, v82
	v_and_or_b32 v80, v81, s28, v80
	v_and_or_b32 v81, v83, s28, v82
	v_lshl_add_u64 v[82:83], s[92:93], 0, v[198:199]
	global_store_dwordx2 v[82:83], v[80:81], off nt

; #define LAS __attribute__((address_space(3)))
; __device__ __forceinline__ unsigned pk2(float lo, float hi) { return f2bf(lo) | (f2bf(hi) << 16); }
; __device__ __forceinline__ f32x4 mfma16(bf16x8 a, bf16x8 b, f32x4 c) { return __builtin_amdgcn_mfma_f32_16x16x32_bf16(a, b, c, 0, 0, 0); }
; __device__ __forceinline__ void gdn_scan_wg(const Ctx& F, int hv, int sl) {
;     ...
;             bf16x8 sf[4];
; #pragma unroll
;             for (int ks = 0; ks < 4; ++ks) sf[ks] = *(const LAS bf16x8*)(Sb + cur * 2176 + fr * 136 + ks * 32 + fq * 8);
;             f32x4 pacc = (f32x4){0.f, 0.f, 0.f, 0.f};
; #pragma unroll
;             for (int ks = 0; ks < 4; ++ks) pacc = mfma16(x.pf[ks], sf[ks], pacc);
;             if (w < 4) {
;                 f32x4 oacc = (f32x4){__uint_as_float(x.ou.x << 16), __uint_as_float(x.ou.x & 0xffff0000u), __uint_as_float(x.ou.y << 16), __uint_as_float(x.ou.y & 0xffff0000u)};
; #pragma unroll
;                 for (int ks = 0; ks < 4; ++ks) oacc = mfma16(sf[ks], x.qf[ks], oacc);
;                 { u32x2 ob; ob.x = pk2(oacc[0], oacc[1]); ob.y = pk2(oacc[2], oacc[3]); *(u32x2*)(O + ((size_t)(hv * 8 + (dv0 >> 4)) * SEQ + (n * 64 + w * 16 + fr)) * 16 + fq * 4) = ob; }
.LBB0_990:
	s_or_b64 exec, exec, s[22:23]
	ds_read_b128 v[124:127], v241
	ds_read_b128 v[128:131], v241 offset:64
	s_and_b64 vcc, exec, s[0:1]
	s_waitcnt vmcnt(19) lgkmcnt(1)
	v_mfma_f32_16x16x32_bf16 v[132:135], v[148:151], v[124:127], 0
	s_waitcnt lgkmcnt(0)
	v_mfma_f32_16x16x32_bf16 v[144:147], v[84:87], v[128:131], v[132:135]
	ds_read_b128 v[84:87], v241 offset:128
	s_nop 4
	ds_read_b128 v[132:135], v241 offset:192
	s_waitcnt lgkmcnt(1)
	v_mfma_f32_16x16x32_bf16 v[72:75], v[72:75], v[84:87], v[144:147]
	s_waitcnt lgkmcnt(0)
	v_mfma_f32_16x16x32_bf16 v[72:75], v[96:99], v[132:135], v[72:75]
	s_cbranch_vccnz .LBB0_992
	s_waitcnt vmcnt(18)
	v_lshlrev_b32_e32 v96, 16, v168
	v_and_b32_e32 v97, 0xffff0000, v168
	v_lshlrev_b32_e32 v98, 16, v169
	v_and_b32_e32 v99, 0xffff0000, v169
	s_nop 1
	v_mfma_f32_16x16x32_bf16 v[96:99], v[124:127], v[32:35], v[96:99]
	v_mfma_f32_16x16x32_bf16 v[96:99], v[128:131], v[36:39], v[96:99]
	v_mfma_f32_16x16x32_bf16 v[84:87], v[84:87], v[40:43], v[96:99]
	v_mfma_f32_16x16x32_bf16 v[84:87], v[132:135], v[44:47], v[84:87]
	s_nop 7
	v_bfe_u32 v96, v84, 16, 1
	v_bfe_u32 v98, v86, 16, 1
	v_bfe_u32 v97, v85, 16, 1
	v_bfe_u32 v99, v87, 16, 1
	v_add3_u32 v84, v84, v96, s29
	v_add3_u32 v86, v86, v98, s29
	v_add3_u32 v85, v85, v97, s29
	v_add3_u32 v87, v87, v99, s29
	v_lshrrev_b32_e32 v84, 16, v84
	v_lshrrev_b32_e32 v86, 16, v86
	v_and_or_b32 v84, v85, s28, v84
	v_and_or_b32 v85, v87, s28, v86
	v_lshl_add_u64 v[86:87], s[92:93], 0, v[196:197]
	global_store_dwordx2 v[86:87], v[84:85], off nt

; #define LAS __attribute__((address_space(3)))
; __device__ __forceinline__ unsigned pk2(float lo, float hi) { return f2bf(lo) | (f2bf(hi) << 16); }
; __device__ __forceinline__ f32x4 mfma16(bf16x8 a, bf16x8 b, f32x4 c) { return __builtin_amdgcn_mfma_f32_16x16x32_bf16(a, b, c, 0, 0, 0); }
; __device__ __forceinline__ void gdn_scan_wg(const Ctx& F, int hv, int sl) {
;     ...
;             bf16x8 sf[4];
; #pragma unroll
;             for (int ks = 0; ks < 4; ++ks) sf[ks] = *(const LAS bf16x8*)(Sb + cur * 2176 + fr * 136 + ks * 32 + fq * 8);
;             f32x4 pacc = (f32x4){0.f, 0.f, 0.f, 0.f};
; #pragma unroll
;             for (int ks = 0; ks < 4; ++ks) pacc = mfma16(x.pf[ks], sf[ks], pacc);
;             if (w < 4) {
;                 f32x4 oacc = (f32x4){__uint_as_float(x.ou.x << 16), __uint_as_float(x.ou.x & 0xffff0000u), __uint_as_float(x.ou.y << 16), __uint_as_float(x.ou.y & 0xffff0000u)};
; #pragma unroll
;                 for (int ks = 0; ks < 4; ++ks) oacc = mfma16(sf[ks], x.qf[ks], oacc);
;                 { u32x2 ob; ob.x = pk2(oacc[0], oacc[1]); ob.y = pk2(oacc[2], oacc[3]); *(u32x2*)(O + ((size_t)(hv * 8 + (dv0 >> 4)) * SEQ + (n * 64 + w * 16 + fr)) * 16 + fq * 4) = ob; }
.LBB0_996:
	s_or_b64 exec, exec, s[22:23]
	ds_read_b128 v[128:131], v241 offset:4352
	ds_read_b128 v[132:135], v241 offset:4416
	s_and_b64 vcc, exec, s[0:1]
	s_waitcnt vmcnt(19) lgkmcnt(1)
	v_mfma_f32_16x16x32_bf16 v[112:115], v[112:115], v[128:131], 0
	s_waitcnt lgkmcnt(0)
	v_mfma_f32_16x16x32_bf16 v[148:151], v[88:91], v[132:135], v[112:115]
	ds_read_b128 v[88:91], v241 offset:4480
	s_nop 4
	ds_read_b128 v[112:115], v241 offset:4544
	s_waitcnt lgkmcnt(1)
	v_mfma_f32_16x16x32_bf16 v[76:79], v[76:79], v[88:91], v[148:151]
	s_waitcnt lgkmcnt(0)
	v_mfma_f32_16x16x32_bf16 v[76:79], v[100:103], v[112:115], v[76:79]
	s_cbranch_vccnz .LBB0_998
	s_waitcnt vmcnt(18)
	v_lshlrev_b32_e32 v100, 16, v208
	v_and_b32_e32 v101, 0xffff0000, v208
	v_lshlrev_b32_e32 v102, 16, v209
	v_and_b32_e32 v103, 0xffff0000, v209
	s_nop 1
	v_mfma_f32_16x16x32_bf16 v[100:103], v[128:131], v[48:51], v[100:103]
	v_mfma_f32_16x16x32_bf16 v[100:103], v[132:135], v[52:55], v[100:103]
	v_mfma_f32_16x16x32_bf16 v[88:91], v[88:91], v[56:59], v[100:103]
	v_mfma_f32_16x16x32_bf16 v[88:91], v[112:115], v[60:63], v[88:91]
	s_nop 7
	v_bfe_u32 v100, v88, 16, 1
	v_bfe_u32 v102, v90, 16, 1
	v_bfe_u32 v101, v89, 16, 1
	v_bfe_u32 v103, v91, 16, 1
	v_add3_u32 v88, v88, v100, s29
	v_add3_u32 v90, v90, v102, s29
	v_add3_u32 v89, v89, v101, s29
	v_add3_u32 v91, v91, v103, s29
	v_lshrrev_b32_e32 v88, 16, v88
	v_lshrrev_b32_e32 v90, 16, v90
	v_and_or_b32 v88, v89, s28, v88
	v_and_or_b32 v89, v91, s28, v90
	v_lshl_add_u64 v[90:91], s[92:93], 0, v[194:195]
	global_store_dwordx2 v[90:91], v[88:89], off nt

; #define LAS __attribute__((address_space(3)))
; __device__ __forceinline__ unsigned pk2(float lo, float hi) { return f2bf(lo) | (f2bf(hi) << 16); }
; __device__ __forceinline__ f32x4 mfma16(bf16x8 a, bf16x8 b, f32x4 c) { return __builtin_amdgcn_mfma_f32_16x16x32_bf16(a, b, c, 0, 0, 0); }
; __device__ __forceinline__ void gdn_scan_wg(const Ctx& F, int hv, int sl) {
;     ...
;             bf16x8 sf[4];
; #pragma unroll
;             for (int ks = 0; ks < 4; ++ks) sf[ks] = *(const LAS bf16x8*)(Sb + cur * 2176 + fr * 136 + ks * 32 + fq * 8);
;             f32x4 pacc = (f32x4){0.f, 0.f, 0.f, 0.f};
; #pragma unroll
;             for (int ks = 0; ks < 4; ++ks) pacc = mfma16(x.pf[ks], sf[ks], pacc);
;             if (w < 4) {
;                 f32x4 oacc = (f32x4){__uint_as_float(x.ou.x << 16), __uint_as_float(x.ou.x & 0xffff0000u), __uint_as_float(x.ou.y << 16), __uint_as_float(x.ou.y & 0xffff0000u)};
; #pragma unroll
;                 for (int ks = 0; ks < 4; ++ks) oacc = mfma16(sf[ks], x.qf[ks], oacc);
;                 { u32x2 ob; ob.x = pk2(oacc[0], oacc[1]); ob.y = pk2(oacc[2], oacc[3]); *(u32x2*)(O + ((size_t)(hv * 8 + (dv0 >> 4)) * SEQ + (n * 64 + w * 16 + fr)) * 16 + fq * 4) = ob; }
.LBB0_1002:
	s_or_b64 exec, exec, s[22:23]
	ds_read_b128 v[112:115], v241
	ds_read_b128 v[132:135], v241 offset:64
	s_and_b64 vcc, exec, s[0:1]
	s_waitcnt vmcnt(19) lgkmcnt(1)
	v_mfma_f32_16x16x32_bf16 v[116:119], v[116:119], v[112:115], 0
	s_waitcnt lgkmcnt(0)
	v_mfma_f32_16x16x32_bf16 v[222:225], v[92:95], v[132:135], v[116:119]
	ds_read_b128 v[92:95], v241 offset:128
	s_nop 4
	ds_read_b128 v[116:119], v241 offset:192
	s_waitcnt lgkmcnt(1)
	v_mfma_f32_16x16x32_bf16 v[64:67], v[64:67], v[92:95], v[222:225]
	s_waitcnt lgkmcnt(0)
	v_mfma_f32_16x16x32_bf16 v[64:67], v[104:107], v[116:119], v[64:67]
	s_cbranch_vccnz .LBB0_1004
	s_waitcnt vmcnt(18)
	v_lshlrev_b32_e32 v104, 16, v156
	v_and_b32_e32 v105, 0xffff0000, v156
	v_lshlrev_b32_e32 v106, 16, v157
	v_and_b32_e32 v107, 0xffff0000, v157
	s_nop 1
	v_mfma_f32_16x16x32_bf16 v[104:107], v[112:115], v[0:3], v[104:107]
	v_mfma_f32_16x16x32_bf16 v[104:107], v[132:135], v[4:7], v[104:107]
	v_mfma_f32_16x16x32_bf16 v[92:95], v[92:95], v[8:11], v[104:107]
	v_mfma_f32_16x16x32_bf16 v[92:95], v[116:119], v[12:15], v[92:95]
	s_nop 7
	v_bfe_u32 v104, v92, 16, 1
	v_bfe_u32 v106, v94, 16, 1
	v_bfe_u32 v105, v93, 16, 1
	v_bfe_u32 v107, v95, 16, 1
	v_add3_u32 v92, v92, v104, s29
	v_add3_u32 v94, v94, v106, s29
	v_add3_u32 v93, v93, v105, s29
	v_add3_u32 v95, v95, v107, s29
	v_lshrrev_b32_e32 v92, 16, v92
	v_lshrrev_b32_e32 v94, 16, v94
	v_and_or_b32 v92, v93, s28, v92
	v_and_or_b32 v93, v95, s28, v94
	v_lshl_add_u64 v[94:95], s[92:93], 0, v[192:193]
	global_store_dwordx2 v[94:95], v[92:93], off nt

; #define LAS __attribute__((address_space(3)))
; __device__ __forceinline__ unsigned pk2(float lo, float hi) { return f2bf(lo) | (f2bf(hi) << 16); }
; __device__ __forceinline__ f32x4 mfma16(bf16x8 a, bf16x8 b, f32x4 c) { return __builtin_amdgcn_mfma_f32_16x16x32_bf16(a, b, c, 0, 0, 0); }
; __device__ __forceinline__ void gdn_scan_wg(const Ctx& F, int hv, int sl) {
;     ...
;             bf16x8 sf[4];
; #pragma unroll
;             for (int ks = 0; ks < 4; ++ks) sf[ks] = *(const LAS bf16x8*)(Sb + cur * 2176 + fr * 136 + ks * 32 + fq * 8);
;             f32x4 pacc = (f32x4){0.f, 0.f, 0.f, 0.f};
; #pragma unroll
;             for (int ks = 0; ks < 4; ++ks) pacc = mfma16(x.pf[ks], sf[ks], pacc);
;             if (w < 4) {
;                 f32x4 oacc = (f32x4){__uint_as_float(x.ou.x << 16), __uint_as_float(x.ou.x & 0xffff0000u), __uint_as_float(x.ou.y << 16), __uint_as_float(x.ou.y & 0xffff0000u)};
; #pragma unroll
;                 for (int ks = 0; ks < 4; ++ks) oacc = mfma16(sf[ks], x.qf[ks], oacc);
;                 { u32x2 ob; ob.x = pk2(oacc[0], oacc[1]); ob.y = pk2(oacc[2], oacc[3]); *(u32x2*)(O + ((size_t)(hv * 8 + (dv0 >> 4)) * SEQ + (n * 64 + w * 16 + fr)) * 16 + fq * 4) = ob; }
.LBB0_1008:
	s_or_b64 exec, exec, s[22:23]
	ds_read_b128 v[112:115], v241 offset:4352
	ds_read_b128 v[132:135], v241 offset:4416
	s_and_b64 vcc, exec, s[0:1]
	s_waitcnt vmcnt(19) lgkmcnt(1)
	v_mfma_f32_16x16x32_bf16 v[120:123], v[120:123], v[112:115], 0
	s_waitcnt lgkmcnt(0)
	v_mfma_f32_16x16x32_bf16 v[228:231], v[80:83], v[132:135], v[120:123]
	ds_read_b128 v[80:83], v241 offset:4480
	s_nop 4
	ds_read_b128 v[120:123], v241 offset:4544
	s_waitcnt lgkmcnt(1)
	v_mfma_f32_16x16x32_bf16 v[68:71], v[68:71], v[80:83], v[228:231]
	s_waitcnt lgkmcnt(0)
	v_mfma_f32_16x16x32_bf16 v[68:71], v[108:111], v[120:123], v[68:71]
	s_cbranch_vccnz .LBB0_1010
	s_waitcnt vmcnt(18)
	v_lshlrev_b32_e32 v108, 16, v158
	v_and_b32_e32 v109, 0xffff0000, v158
	v_lshlrev_b32_e32 v110, 16, v159
	v_and_b32_e32 v111, 0xffff0000, v159
	s_nop 1
	v_mfma_f32_16x16x32_bf16 v[108:111], v[112:115], v[16:19], v[108:111]
	v_mfma_f32_16x16x32_bf16 v[108:111], v[132:135], v[20:23], v[108:111]
	v_mfma_f32_16x16x32_bf16 v[80:83], v[80:83], v[24:27], v[108:111]
	v_mfma_f32_16x16x32_bf16 v[80:83], v[120:123], v[28:31], v[80:83]
	s_nop 7
	v_bfe_u32 v108, v80, 16, 1
	v_bfe_u32 v110, v82, 16, 1
	v_bfe_u32 v109, v81, 16, 1
	v_bfe_u32 v111, v83, 16, 1
	v_add3_u32 v80, v80, v108, s29
	v_add3_u32 v82, v82, v110, s29
	v_add3_u32 v81, v81, v109, s29
	v_add3_u32 v83, v83, v111, s29
	v_lshrrev_b32_e32 v80, 16, v80
	v_lshrrev_b32_e32 v82, 16, v82
	v_and_or_b32 v80, v81, s28, v80
	v_and_or_b32 v81, v83, s28, v82
	v_lshl_add_u64 v[82:83], s[92:93], 0, v[190:191]
	global_store_dwordx2 v[82:83], v[80:81], off nt

; #define LAS __attribute__((address_space(3)))
; __device__ __forceinline__ unsigned pk2(float lo, float hi) { return f2bf(lo) | (f2bf(hi) << 16); }
; __device__ __forceinline__ f32x4 mfma16(bf16x8 a, bf16x8 b, f32x4 c) { return __builtin_amdgcn_mfma_f32_16x16x32_bf16(a, b, c, 0, 0, 0); }
; __device__ __forceinline__ void gdn_scan_wg(const Ctx& F, int hv, int sl) {
;     ...
;             bf16x8 sf[4];
; #pragma unroll
;             for (int ks = 0; ks < 4; ++ks) sf[ks] = *(const LAS bf16x8*)(Sb + cur * 2176 + fr * 136 + ks * 32 + fq * 8);
;             f32x4 pacc = (f32x4){0.f, 0.f, 0.f, 0.f};
; #pragma unroll
;             for (int ks = 0; ks < 4; ++ks) pacc = mfma16(x.pf[ks], sf[ks], pacc);
;             if (w < 4) {
;                 f32x4 oacc = (f32x4){__uint_as_float(x.ou.x << 16), __uint_as_float(x.ou.x & 0xffff0000u), __uint_as_float(x.ou.y << 16), __uint_as_float(x.ou.y & 0xffff0000u)};
; #pragma unroll
;                 for (int ks = 0; ks < 4; ++ks) oacc = mfma16(sf[ks], x.qf[ks], oacc);
;                 { u32x2 ob; ob.x = pk2(oacc[0], oacc[1]); ob.y = pk2(oacc[2], oacc[3]); *(u32x2*)(O + ((size_t)(hv * 8 + (dv0 >> 4)) * SEQ + (n * 64 + w * 16 + fr)) * 16 + fq * 4) = ob; }
.LBB0_1014:
	s_or_b64 exec, exec, s[22:23]
	ds_read_b128 v[120:123], v241
	ds_read_b128 v[136:139], v241 offset:64
	s_and_b64 vcc, exec, s[0:1]
	s_waitcnt vmcnt(19) lgkmcnt(1)
	v_mfma_f32_16x16x32_bf16 v[68:71], v[124:127], v[120:123], 0
	s_waitcnt lgkmcnt(0)
	v_mfma_f32_16x16x32_bf16 v[68:71], v[84:87], v[136:139], v[68:71]
	ds_read_b128 v[84:87], v241 offset:128
	ds_read_b128 v[124:127], v241 offset:192
	s_waitcnt lgkmcnt(1)
	v_mfma_f32_16x16x32_bf16 v[68:71], v[72:75], v[84:87], v[68:71]
	s_waitcnt lgkmcnt(0)
	v_mfma_f32_16x16x32_bf16 v[68:71], v[96:99], v[124:127], v[68:71]
	s_cbranch_vccnz .LBB0_1016
	s_waitcnt vmcnt(18)
	v_lshlrev_b32_e32 v72, 16, v168
	v_and_b32_e32 v73, 0xffff0000, v168
	v_lshlrev_b32_e32 v74, 16, v169
	v_and_b32_e32 v75, 0xffff0000, v169
	s_nop 1
	v_mfma_f32_16x16x32_bf16 v[72:75], v[120:123], v[32:35], v[72:75]
	v_mfma_f32_16x16x32_bf16 v[72:75], v[136:139], v[36:39], v[72:75]
	v_mfma_f32_16x16x32_bf16 v[72:75], v[84:87], v[40:43], v[72:75]
	v_mfma_f32_16x16x32_bf16 v[72:75], v[124:127], v[44:47], v[72:75]
	s_nop 7
	v_bfe_u32 v84, v72, 16, 1
	v_bfe_u32 v86, v74, 16, 1
	v_bfe_u32 v85, v73, 16, 1
	v_bfe_u32 v87, v75, 16, 1
	v_add3_u32 v72, v72, v84, s29
	v_add3_u32 v74, v74, v86, s29
	v_add3_u32 v73, v73, v85, s29
	v_add3_u32 v75, v75, v87, s29
	v_lshrrev_b32_e32 v72, 16, v72
	v_lshrrev_b32_e32 v74, 16, v74
	v_and_or_b32 v72, v73, s28, v72
	v_and_or_b32 v73, v75, s28, v74
	v_lshl_add_u64 v[74:75], s[92:93], 0, v[188:189]
	global_store_dwordx2 v[74:75], v[72:73], off nt

; #define LAS __attribute__((address_space(3)))
; __device__ __forceinline__ unsigned pk2(float lo, float hi) { return f2bf(lo) | (f2bf(hi) << 16); }
; __device__ __forceinline__ f32x4 mfma16(bf16x8 a, bf16x8 b, f32x4 c) { return __builtin_amdgcn_mfma_f32_16x16x32_bf16(a, b, c, 0, 0, 0); }
; __device__ __forceinline__ void gdn_scan_wg(const Ctx& F, int hv, int sl) {
;     ...
;             bf16x8 sf[4];
; #pragma unroll
;             for (int ks = 0; ks < 4; ++ks) sf[ks] = *(const LAS bf16x8*)(Sb + cur * 2176 + fr * 136 + ks * 32 + fq * 8);
;             f32x4 pacc = (f32x4){0.f, 0.f, 0.f, 0.f};
; #pragma unroll
;             for (int ks = 0; ks < 4; ++ks) pacc = mfma16(x.pf[ks], sf[ks], pacc);
;             if (w < 4) {
;                 f32x4 oacc = (f32x4){__uint_as_float(x.ou.x << 16), __uint_as_float(x.ou.x & 0xffff0000u), __uint_as_float(x.ou.y << 16), __uint_as_float(x.ou.y & 0xffff0000u)};
; #pragma unroll
;                 for (int ks = 0; ks < 4; ++ks) oacc = mfma16(sf[ks], x.qf[ks], oacc);
;                 { u32x2 ob; ob.x = pk2(oacc[0], oacc[1]); ob.y = pk2(oacc[2], oacc[3]); *(u32x2*)(O + ((size_t)(hv * 8 + (dv0 >> 4)) * SEQ + (n * 64 + w * 16 + fr)) * 16 + fq * 4) = ob; }
.LBB0_1020:
	s_or_b64 exec, exec, s[22:23]
	ds_read_b128 v[72:75], v241 offset:4352
	ds_read_b128 v[84:87], v241 offset:4416
	s_and_b64 vcc, exec, s[0:1]
	s_waitcnt vmcnt(19) lgkmcnt(1)
	v_mfma_f32_16x16x32_bf16 v[68:71], v[128:131], v[72:75], 0
	s_waitcnt lgkmcnt(0)
	v_mfma_f32_16x16x32_bf16 v[68:71], v[88:91], v[84:87], v[68:71]
	ds_read_b128 v[88:91], v241 offset:4480
	ds_read_b128 v[128:131], v241 offset:4544
	s_waitcnt lgkmcnt(1)
	v_mfma_f32_16x16x32_bf16 v[68:71], v[76:79], v[88:91], v[68:71]
	s_waitcnt lgkmcnt(0)
	v_mfma_f32_16x16x32_bf16 v[68:71], v[100:103], v[128:131], v[68:71]
	s_cbranch_vccnz .LBB0_1022
	s_waitcnt vmcnt(18)
	v_lshlrev_b32_e32 v76, 16, v208
	v_and_b32_e32 v77, 0xffff0000, v208
	v_lshlrev_b32_e32 v78, 16, v209
	v_and_b32_e32 v79, 0xffff0000, v209
	s_nop 1
	v_mfma_f32_16x16x32_bf16 v[72:75], v[72:75], v[48:51], v[76:79]
	v_mfma_f32_16x16x32_bf16 v[72:75], v[84:87], v[52:55], v[72:75]
	v_mfma_f32_16x16x32_bf16 v[72:75], v[88:91], v[56:59], v[72:75]
	v_mfma_f32_16x16x32_bf16 v[72:75], v[128:131], v[60:63], v[72:75]
	s_nop 7
	v_bfe_u32 v76, v72, 16, 1
	v_bfe_u32 v78, v74, 16, 1
	v_bfe_u32 v77, v73, 16, 1
	v_bfe_u32 v79, v75, 16, 1
	v_add3_u32 v72, v72, v76, s29
	v_add3_u32 v74, v74, v78, s29
	v_add3_u32 v73, v73, v77, s29
	v_add3_u32 v75, v75, v79, s29
	v_lshrrev_b32_e32 v72, 16, v72
	v_lshrrev_b32_e32 v74, 16, v74
	v_and_or_b32 v72, v73, s28, v72
	v_and_or_b32 v73, v75, s28, v74
	v_lshl_add_u64 v[74:75], s[92:93], 0, v[186:187]
	global_store_dwordx2 v[74:75], v[72:73], off nt

; #define LAS __attribute__((address_space(3)))
; __device__ __forceinline__ unsigned pk2(float lo, float hi) { return f2bf(lo) | (f2bf(hi) << 16); }
; __device__ __forceinline__ f32x4 mfma16(bf16x8 a, bf16x8 b, f32x4 c) { return __builtin_amdgcn_mfma_f32_16x16x32_bf16(a, b, c, 0, 0, 0); }
; __device__ __forceinline__ void gdn_scan_wg(const Ctx& F, int hv, int sl) {
;     ...
;             bf16x8 sf[4];
; #pragma unroll
;             for (int ks = 0; ks < 4; ++ks) sf[ks] = *(const LAS bf16x8*)(Sb + cur * 2176 + fr * 136 + ks * 32 + fq * 8);
;             f32x4 pacc = (f32x4){0.f, 0.f, 0.f, 0.f};
; #pragma unroll
;             for (int ks = 0; ks < 4; ++ks) pacc = mfma16(x.pf[ks], sf[ks], pacc);
;             if (w < 4) {
;                 f32x4 oacc = (f32x4){__uint_as_float(x.ou.x << 16), __uint_as_float(x.ou.x & 0xffff0000u), __uint_as_float(x.ou.y << 16), __uint_as_float(x.ou.y & 0xffff0000u)};
; #pragma unroll
;                 for (int ks = 0; ks < 4; ++ks) oacc = mfma16(sf[ks], x.qf[ks], oacc);
;                 { u32x2 ob; ob.x = pk2(oacc[0], oacc[1]); ob.y = pk2(oacc[2], oacc[3]); *(u32x2*)(O + ((size_t)(hv * 8 + (dv0 >> 4)) * SEQ + (n * 64 + w * 16 + fr)) * 16 + fq * 4) = ob; }
.LBB0_1026:
	s_or_b64 exec, exec, s[20:21]
	ds_read_b128 v[68:71], v241
	ds_read_b128 v[72:75], v241 offset:64
	s_and_b64 vcc, exec, s[0:1]
	s_waitcnt vmcnt(19) lgkmcnt(1)
	v_mfma_f32_16x16x32_bf16 v[76:79], v[116:119], v[68:71], 0
	s_waitcnt lgkmcnt(0)
	v_mfma_f32_16x16x32_bf16 v[92:95], v[92:95], v[72:75], v[76:79]
	s_nop 5
	ds_read_b128 v[76:79], v241 offset:128
	ds_read_b128 v[84:87], v241 offset:192
	s_waitcnt lgkmcnt(1)
	v_mfma_f32_16x16x32_bf16 v[64:67], v[64:67], v[76:79], v[92:95]
	s_waitcnt lgkmcnt(0)
	v_mfma_f32_16x16x32_bf16 v[64:67], v[104:107], v[84:87], v[64:67]
	s_cbranch_vccnz .LBB0_1028
	s_waitcnt vmcnt(18)
	v_lshlrev_b32_e32 v92, 16, v156
	v_and_b32_e32 v93, 0xffff0000, v156
	v_lshlrev_b32_e32 v94, 16, v157
	v_and_b32_e32 v95, 0xffff0000, v157
	s_nop 1
	v_mfma_f32_16x16x32_bf16 v[68:71], v[68:71], v[0:3], v[92:95]
	v_mfma_f32_16x16x32_bf16 v[68:71], v[72:75], v[4:7], v[68:71]
	v_mfma_f32_16x16x32_bf16 v[68:71], v[76:79], v[8:11], v[68:71]
	v_mfma_f32_16x16x32_bf16 v[68:71], v[84:87], v[12:15], v[68:71]
	s_nop 7
	v_bfe_u32 v72, v68, 16, 1
	v_bfe_u32 v74, v70, 16, 1
	v_bfe_u32 v73, v69, 16, 1
	v_bfe_u32 v75, v71, 16, 1
	v_add3_u32 v68, v68, v72, s29
	v_add3_u32 v70, v70, v74, s29
	v_add3_u32 v69, v69, v73, s29
	v_add3_u32 v71, v71, v75, s29
	v_lshrrev_b32_e32 v68, 16, v68
	v_lshrrev_b32_e32 v70, 16, v70
	v_and_or_b32 v68, v69, s28, v68
	v_and_or_b32 v69, v71, s28, v70
	v_lshl_add_u64 v[70:71], s[92:93], 0, v[176:177]
	global_store_dwordx2 v[70:71], v[68:69], off nt

; #define LAS __attribute__((address_space(3)))
; __device__ __forceinline__ unsigned pk2(float lo, float hi) { return f2bf(lo) | (f2bf(hi) << 16); }
; __device__ __forceinline__ f32x4 mfma16(bf16x8 a, bf16x8 b, f32x4 c) { return __builtin_amdgcn_mfma_f32_16x16x32_bf16(a, b, c, 0, 0, 0); }
; __device__ __forceinline__ void gdn_scan_wg(const Ctx& F, int hv, int sl) {
;     ...
;             bf16x8 sf[4];
; #pragma unroll
;             for (int ks = 0; ks < 4; ++ks) sf[ks] = *(const LAS bf16x8*)(Sb + cur * 2176 + fr * 136 + ks * 32 + fq * 8);
;             f32x4 pacc = (f32x4){0.f, 0.f, 0.f, 0.f};
; #pragma unroll
;             for (int ks = 0; ks < 4; ++ks) pacc = mfma16(x.pf[ks], sf[ks], pacc);
;             if (w < 4) {
;                 f32x4 oacc = (f32x4){__uint_as_float(x.ou.x << 16), __uint_as_float(x.ou.x & 0xffff0000u), __uint_as_float(x.ou.y << 16), __uint_as_float(x.ou.y & 0xffff0000u)};
; #pragma unroll
;                 for (int ks = 0; ks < 4; ++ks) oacc = mfma16(sf[ks], x.qf[ks], oacc);
;                 { u32x2 ob; ob.x = pk2(oacc[0], oacc[1]); ob.y = pk2(oacc[2], oacc[3]); *(u32x2*)(O + ((size_t)(hv * 8 + (dv0 >> 4)) * SEQ + (n * 64 + w * 16 + fr)) * 16 + fq * 4) = ob; }
.LBB0_1032:
	s_or_b64 exec, exec, s[20:21]
	ds_read_b128 v[84:87], v241 offset:4352
	ds_read_b128 v[88:91], v241 offset:4416
	s_and_b64 vcc, exec, s[0:1]
	s_waitcnt vmcnt(19) lgkmcnt(1)
	v_mfma_f32_16x16x32_bf16 v[92:95], v[132:135], v[84:87], 0
	s_waitcnt lgkmcnt(0)
	v_mfma_f32_16x16x32_bf16 v[108:111], v[108:111], v[88:91], v[92:95]
	s_nop 5
	ds_read_b128 v[92:95], v241 offset:4480
	ds_read_b128 v[100:103], v241 offset:4544
	s_waitcnt lgkmcnt(1)
	v_mfma_f32_16x16x32_bf16 v[80:83], v[80:83], v[92:95], v[108:111]
	s_waitcnt lgkmcnt(0)
	v_mfma_f32_16x16x32_bf16 v[80:83], v[112:115], v[100:103], v[80:83]
	s_cbranch_vccnz .LBB0_1034
	s_waitcnt vmcnt(18)
	v_lshlrev_b32_e32 v108, 16, v158
	v_and_b32_e32 v109, 0xffff0000, v158
	v_lshlrev_b32_e32 v110, 16, v159
	v_and_b32_e32 v111, 0xffff0000, v159
	s_nop 1
	v_mfma_f32_16x16x32_bf16 v[84:87], v[84:87], v[16:19], v[108:111]
	v_mfma_f32_16x16x32_bf16 v[84:87], v[88:91], v[20:23], v[84:87]
	v_mfma_f32_16x16x32_bf16 v[84:87], v[92:95], v[24:27], v[84:87]
	v_mfma_f32_16x16x32_bf16 v[84:87], v[100:103], v[28:31], v[84:87]
	s_nop 7
	v_bfe_u32 v88, v84, 16, 1
	v_bfe_u32 v90, v86, 16, 1
	v_bfe_u32 v89, v85, 16, 1
	v_bfe_u32 v91, v87, 16, 1
	v_add3_u32 v84, v84, v88, s29
	v_add3_u32 v86, v86, v90, s29
	v_add3_u32 v85, v85, v89, s29
	v_add3_u32 v87, v87, v91, s29
	v_lshrrev_b32_e32 v84, 16, v84
	v_lshrrev_b32_e32 v86, 16, v86
	v_and_or_b32 v84, v85, s28, v84
	v_and_or_b32 v85, v87, s28, v86
	v_lshl_add_u64 v[86:87], s[92:93], 0, v[174:175]
	global_store_dwordx2 v[86:87], v[84:85], off nt

; #define LAS __attribute__((address_space(3)))
; __device__ __forceinline__ unsigned pk2(float lo, float hi) { return f2bf(lo) | (f2bf(hi) << 16); }
; __device__ __forceinline__ f32x4 mfma16(bf16x8 a, bf16x8 b, f32x4 c) { return __builtin_amdgcn_mfma_f32_16x16x32_bf16(a, b, c, 0, 0, 0); }
; __device__ __forceinline__ void gdn_scan_wg(const Ctx& F, int hv, int sl) {
;     ...
;             bf16x8 sf[4];
; #pragma unroll
;             for (int ks = 0; ks < 4; ++ks) sf[ks] = *(const LAS bf16x8*)(Sb + cur * 2176 + fr * 136 + ks * 32 + fq * 8);
;             f32x4 pacc = (f32x4){0.f, 0.f, 0.f, 0.f};
; #pragma unroll
;             for (int ks = 0; ks < 4; ++ks) pacc = mfma16(x.pf[ks], sf[ks], pacc);
;             if (w < 4) {
;                 f32x4 oacc = (f32x4){__uint_as_float(x.ou.x << 16), __uint_as_float(x.ou.x & 0xffff0000u), __uint_as_float(x.ou.y << 16), __uint_as_float(x.ou.y & 0xffff0000u)};
; #pragma unroll
;                 for (int ks = 0; ks < 4; ++ks) oacc = mfma16(sf[ks], x.qf[ks], oacc);
;                 { u32x2 ob; ob.x = pk2(oacc[0], oacc[1]); ob.y = pk2(oacc[2], oacc[3]); *(u32x2*)(O + ((size_t)(hv * 8 + (dv0 >> 4)) * SEQ + (n * 64 + w * 16 + fr)) * 16 + fq * 4) = ob; }
.LBB0_1038:
	s_or_b64 exec, exec, s[20:21]
	ds_read_b128 v[100:103], v241
	ds_read_b128 v[104:107], v241 offset:64
	s_and_b64 vcc, exec, s[0:1]
	s_waitcnt vmcnt(19) lgkmcnt(1)
	v_mfma_f32_16x16x32_bf16 v[108:111], v[144:147], v[100:103], 0
	s_waitcnt lgkmcnt(0)
	v_mfma_f32_16x16x32_bf16 v[120:123], v[120:123], v[104:107], v[108:111]
	s_nop 5
	ds_read_b128 v[108:111], v241 offset:128
	ds_read_b128 v[112:115], v241 offset:192
	s_waitcnt lgkmcnt(1)
	v_mfma_f32_16x16x32_bf16 v[96:99], v[96:99], v[108:111], v[120:123]
	s_waitcnt lgkmcnt(0)
	v_mfma_f32_16x16x32_bf16 v[96:99], v[124:127], v[112:115], v[96:99]
	s_cbranch_vccnz .LBB0_1040
	s_waitcnt vmcnt(18)
	v_lshlrev_b32_e32 v120, 16, v168
	v_and_b32_e32 v121, 0xffff0000, v168
	v_lshlrev_b32_e32 v122, 16, v169
	v_and_b32_e32 v123, 0xffff0000, v169
	s_nop 1
	v_mfma_f32_16x16x32_bf16 v[100:103], v[100:103], v[32:35], v[120:123]
	v_mfma_f32_16x16x32_bf16 v[100:103], v[104:107], v[36:39], v[100:103]
	v_mfma_f32_16x16x32_bf16 v[100:103], v[108:111], v[40:43], v[100:103]
	v_mfma_f32_16x16x32_bf16 v[100:103], v[112:115], v[44:47], v[100:103]
	s_nop 7
	v_bfe_u32 v104, v100, 16, 1
	v_bfe_u32 v106, v102, 16, 1
	v_bfe_u32 v105, v101, 16, 1
	v_bfe_u32 v107, v103, 16, 1
	v_add3_u32 v100, v100, v104, s29
	v_add3_u32 v102, v102, v106, s29
	v_add3_u32 v101, v101, v105, s29
	v_add3_u32 v103, v103, v107, s29
	v_lshrrev_b32_e32 v100, 16, v100
	v_lshrrev_b32_e32 v102, 16, v102
	v_and_or_b32 v100, v101, s28, v100
	v_and_or_b32 v101, v103, s28, v102
	v_lshl_add_u64 v[102:103], s[92:93], 0, v[172:173]
	global_store_dwordx2 v[102:103], v[100:101], off nt

; #define LAS __attribute__((address_space(3)))
; __device__ __forceinline__ unsigned pk2(float lo, float hi) { return f2bf(lo) | (f2bf(hi) << 16); }
; __device__ __forceinline__ f32x4 mfma16(bf16x8 a, bf16x8 b, f32x4 c) { return __builtin_amdgcn_mfma_f32_16x16x32_bf16(a, b, c, 0, 0, 0); }
; __device__ __forceinline__ void gdn_scan_wg(const Ctx& F, int hv, int sl) {
;     ...
;             bf16x8 sf[4];
; #pragma unroll
;             for (int ks = 0; ks < 4; ++ks) sf[ks] = *(const LAS bf16x8*)(Sb + cur * 2176 + fr * 136 + ks * 32 + fq * 8);
;             f32x4 pacc = (f32x4){0.f, 0.f, 0.f, 0.f};
; #pragma unroll
;             for (int ks = 0; ks < 4; ++ks) pacc = mfma16(x.pf[ks], sf[ks], pacc);
;             if (w < 4) {
;                 f32x4 oacc = (f32x4){__uint_as_float(x.ou.x << 16), __uint_as_float(x.ou.x & 0xffff0000u), __uint_as_float(x.ou.y << 16), __uint_as_float(x.ou.y & 0xffff0000u)};
; #pragma unroll
;                 for (int ks = 0; ks < 4; ++ks) oacc = mfma16(sf[ks], x.qf[ks], oacc);
;                 { u32x2 ob; ob.x = pk2(oacc[0], oacc[1]); ob.y = pk2(oacc[2], oacc[3]); *(u32x2*)(O + ((size_t)(hv * 8 + (dv0 >> 4)) * SEQ + (n * 64 + w * 16 + fr)) * 16 + fq * 4) = ob; }
.LBB0_1044:
	s_or_b64 exec, exec, s[20:21]
	ds_read_b128 v[116:119], v241 offset:4352
	ds_read_b128 v[120:123], v241 offset:4416
	ds_read_b128 v[124:127], v241 offset:4480
	ds_read_b128 v[132:135], v241 offset:4544
	s_and_b64 vcc, exec, s[0:1]
	s_waitcnt vmcnt(19) lgkmcnt(3)
	v_mfma_f32_16x16x32_bf16 v[112:115], v[148:151], v[116:119], 0
	s_waitcnt lgkmcnt(2)
	v_mfma_f32_16x16x32_bf16 v[112:115], v[136:139], v[120:123], v[112:115]
	s_waitcnt lgkmcnt(1)
	v_mfma_f32_16x16x32_bf16 v[112:115], v[128:131], v[124:127], v[112:115]
	s_waitcnt lgkmcnt(0)
	v_mfma_f32_16x16x32_bf16 v[112:115], v[140:143], v[132:135], v[112:115]
	s_cbranch_vccnz .LBB0_949
	s_waitcnt vmcnt(18)
	v_lshlrev_b32_e32 v128, 16, v208
	v_and_b32_e32 v129, 0xffff0000, v208
	v_lshlrev_b32_e32 v130, 16, v209
	v_and_b32_e32 v131, 0xffff0000, v209
	s_nop 1
	v_mfma_f32_16x16x32_bf16 v[116:119], v[116:119], v[48:51], v[128:131]
	v_mfma_f32_16x16x32_bf16 v[116:119], v[120:123], v[52:55], v[116:119]
	v_mfma_f32_16x16x32_bf16 v[116:119], v[124:127], v[56:59], v[116:119]
	v_mfma_f32_16x16x32_bf16 v[116:119], v[132:135], v[60:63], v[116:119]
	s_nop 7
	v_bfe_u32 v120, v116, 16, 1
	v_bfe_u32 v122, v118, 16, 1
	v_bfe_u32 v121, v117, 16, 1
	v_bfe_u32 v123, v119, 16, 1
	v_add3_u32 v116, v116, v120, s29
	v_add3_u32 v118, v118, v122, s29
	v_add3_u32 v117, v117, v121, s29
	v_add3_u32 v119, v119, v123, s29
	v_lshrrev_b32_e32 v116, 16, v116
	v_lshrrev_b32_e32 v118, 16, v118
	v_and_or_b32 v116, v117, s28, v116
	v_and_or_b32 v117, v119, s28, v118
	v_lshl_add_u64 v[118:119], s[92:93], 0, v[170:171]
	global_store_dwordx2 v[118:119], v[116:117], off nt
	s_branch .LBB0_949

; #define LAS __attribute__((address_space(3)))
; template <bool POST, bool PRE>
; __device__ __forceinline__ void row_core(const Params& P, const RowCfg& c, LAS float* vA, LAS float* vB, LAS float* vP, const bf16_t* RAW, const float* SSQ, bf16_t* H, int row, int lane, f32x4 (&v)[8]) {
;     ...
;         const u32x2* rs = (const u32x2*)(RAW + (size_t)row * DM) + lane;
;         float s = (lane < 32) ? SSQ[(size_t)row * 32 + lane] : 0.f; s = wave_sum(s);
;         const float rstd = rsqrtf(s * (1.0f / DM) + EPS);
;         f32x4* os = (f32x4*)(P.out + (size_t)row * DM) + lane;
; #pragma unroll
;         for (int j = 0; j < 8; ++j) { const u32x2 rb = rs[64 * j]; const f32x4 r = (f32x4){__uint_as_float(rb.x << 16), __uint_as_float(rb.x & 0xffff0000u), __uint_as_float(rb.y << 16), __uint_as_float(rb.y & 0xffff0000u)};
;             const f32x4 pv = *(const LAS f32x4*)(vP + j * 256 + lane * 4); v[j] += r * rstd * pv; os[64 * j] = v[j]; }
.LBB0_1508:
	s_or_b64 exec, exec, s[42:43]
	s_lshl_b64 s[42:43], s[38:39], 11
	s_lshl_b64 s[42:43], s[42:43], 1
	v_lshl_add_u64 v[86:87], v[48:49], 0, s[42:43]
	global_load_dwordx2 v[96:97], v[86:87], off
	s_waitcnt vmcnt(1)
	ds_bpermute_b32 v85, v106, v84
	ds_read_b128 v[88:91], v112 offset:16384
	ds_read_b128 v[92:95], v112 offset:17408
	v_lshl_add_u64 v[186:187], v[50:51], 0, s[42:43]
	s_waitcnt lgkmcnt(2)
	v_add_f32_e32 v84, v84, v85
	ds_bpermute_b32 v85, v107, v84
	s_waitcnt lgkmcnt(0)
	v_add_f32_e32 v84, v84, v85
	ds_bpermute_b32 v85, v108, v84
	s_waitcnt lgkmcnt(0)
	v_add_f32_e32 v84, v84, v85
	ds_bpermute_b32 v85, v109, v84
	s_waitcnt lgkmcnt(0)
	v_add_f32_e32 v84, v84, v85
	ds_bpermute_b32 v85, v110, v84
	s_waitcnt lgkmcnt(0)
	v_add_f32_e32 v84, v84, v85
	ds_bpermute_b32 v85, v111, v84
	s_waitcnt lgkmcnt(0)
	v_add_f32_e32 v84, v84, v85
	v_fmamk_f32 v84, v84, 0x3a000000, v178
	v_mul_f32_e32 v85, 0x4b800000, v84
	v_cmp_gt_f32_e32 vcc, s17, v84
	s_waitcnt vmcnt(0)
	v_lshlrev_b32_e32 v98, 16, v96
	v_cndmask_b32_e32 v84, v84, v85, vcc
	v_rsq_f32_e32 v84, v84
	v_and_b32_e32 v99, 0xffff0000, v96
	v_lshlrev_b32_e32 v96, 16, v97
	v_and_b32_e32 v97, 0xffff0000, v97
	v_mul_f32_e32 v85, 0x45800000, v84
	v_cndmask_b32_e32 v84, v84, v85, vcc
	v_pk_mul_f32 v[98:99], v[84:85], v[98:99] op_sel_hi:[0,1]
	v_pk_mul_f32 v[96:97], v[84:85], v[96:97] op_sel_hi:[0,1]
	v_pk_fma_f32 v[10:11], v[90:91], v[96:97], v[10:11]
	v_pk_fma_f32 v[8:9], v[88:89], v[98:99], v[8:9]
	global_store_dwordx4 v[82:83], v[8:11], off nt
	global_load_dwordx2 v[88:89], v[86:87], off offset:512
	s_waitcnt vmcnt(0)
	v_lshlrev_b32_e32 v90, 16, v88
	v_and_b32_e32 v91, 0xffff0000, v88
	v_lshlrev_b32_e32 v88, 16, v89
	v_and_b32_e32 v89, 0xffff0000, v89
	v_pk_mul_f32 v[90:91], v[84:85], v[90:91] op_sel_hi:[0,1]
	v_pk_mul_f32 v[88:89], v[84:85], v[88:89] op_sel_hi:[0,1]
	v_pk_fma_f32 v[6:7], v[94:95], v[88:89], v[6:7]
	v_pk_fma_f32 v[4:5], v[92:93], v[90:91], v[4:5]
	global_store_dwordx4 v[82:83], v[4:7], off offset:1024 nt
	global_load_dwordx2 v[96:97], v[86:87], off offset:1024
	ds_read_b128 v[88:91], v112 offset:18432
	ds_read_b128 v[92:95], v112 offset:19456
	s_waitcnt vmcnt(0)
	v_lshlrev_b32_e32 v98, 16, v96
	v_and_b32_e32 v99, 0xffff0000, v96
	v_lshlrev_b32_e32 v96, 16, v97
	v_and_b32_e32 v97, 0xffff0000, v97
	v_pk_mul_f32 v[98:99], v[84:85], v[98:99] op_sel_hi:[0,1]
	v_pk_mul_f32 v[96:97], v[84:85], v[96:97] op_sel_hi:[0,1]
	s_waitcnt lgkmcnt(1)
	v_pk_fma_f32 v[18:19], v[90:91], v[96:97], v[18:19]
	v_pk_fma_f32 v[16:17], v[88:89], v[98:99], v[16:17]
	global_store_dwordx4 v[82:83], v[16:19], off offset:2048 nt
	global_load_dwordx2 v[88:89], v[86:87], off offset:1536
	v_lshl_add_u64 v[98:99], v[82:83], 0, s[24:25]
	s_waitcnt vmcnt(0)
	v_lshlrev_b32_e32 v90, 16, v88
	v_and_b32_e32 v91, 0xffff0000, v88
	v_lshlrev_b32_e32 v88, 16, v89
	v_and_b32_e32 v89, 0xffff0000, v89
	v_pk_mul_f32 v[90:91], v[84:85], v[90:91] op_sel_hi:[0,1]
	v_pk_mul_f32 v[88:89], v[84:85], v[88:89] op_sel_hi:[0,1]
	s_waitcnt lgkmcnt(0)
	v_pk_fma_f32 v[14:15], v[94:95], v[88:89], v[14:15]
	v_pk_fma_f32 v[12:13], v[92:93], v[90:91], v[12:13]
	global_store_dwordx4 v[82:83], v[12:15], off offset:3072 nt
	global_load_dwordx2 v[96:97], v[86:87], off offset:2048
	ds_read_b128 v[88:91], v112 offset:20480
	ds_read_b128 v[92:95], v112 offset:21504
	s_waitcnt vmcnt(0)
	v_lshlrev_b32_e32 v100, 16, v96
	v_and_b32_e32 v101, 0xffff0000, v96
	v_lshlrev_b32_e32 v96, 16, v97
	v_and_b32_e32 v97, 0xffff0000, v97
	v_pk_mul_f32 v[100:101], v[84:85], v[100:101] op_sel_hi:[0,1]
	v_pk_mul_f32 v[96:97], v[84:85], v[96:97] op_sel_hi:[0,1]
	s_waitcnt lgkmcnt(1)
	v_pk_fma_f32 v[26:27], v[90:91], v[96:97], v[26:27]
	v_pk_fma_f32 v[24:25], v[88:89], v[100:101], v[24:25]
	global_store_dwordx4 v[98:99], v[24:27], off nt
	global_load_dwordx2 v[88:89], v[86:87], off offset:2560
	v_lshl_add_u64 v[90:91], v[82:83], 0, s[30:31]
	v_lshl_add_u64 v[98:99], v[82:83], 0, s[34:35]
	s_waitcnt vmcnt(0)
	v_lshlrev_b32_e32 v96, 16, v88
	v_and_b32_e32 v97, 0xffff0000, v88
	v_lshlrev_b32_e32 v88, 16, v89
	v_and_b32_e32 v89, 0xffff0000, v89
	v_pk_mul_f32 v[96:97], v[84:85], v[96:97] op_sel_hi:[0,1]
	v_pk_mul_f32 v[88:89], v[84:85], v[88:89] op_sel_hi:[0,1]
	s_waitcnt lgkmcnt(0)
	v_pk_fma_f32 v[22:23], v[94:95], v[88:89], v[22:23]
	v_pk_fma_f32 v[20:21], v[92:93], v[96:97], v[20:21]
	global_store_dwordx4 v[90:91], v[20:23], off nt
	global_load_dwordx2 v[96:97], v[86:87], off offset:3072
	ds_read_b128 v[88:91], v112 offset:22528
	ds_read_b128 v[92:95], v112 offset:23552
	s_waitcnt vmcnt(0)
	v_lshlrev_b32_e32 v100, 16, v96
	v_and_b32_e32 v101, 0xffff0000, v96
	v_lshlrev_b32_e32 v96, 16, v97
	v_and_b32_e32 v97, 0xffff0000, v97
	v_pk_mul_f32 v[100:101], v[84:85], v[100:101] op_sel_hi:[0,1]
	v_pk_mul_f32 v[96:97], v[84:85], v[96:97] op_sel_hi:[0,1]
	s_waitcnt lgkmcnt(1)
; #define LAS __attribute__((address_space(3)))
; __device__ __forceinline__ unsigned cvt_pk_bf16(float lo, float hi) { unsigned r; asm volatile("v_cvt_pk_bf16_f32 %0, %1, %2" : "=v"(r) : "v"(lo), "v"(hi)); return r; }
; __device__ __forceinline__ float wave_sum(float v) {
; #pragma unroll
;     for (int o = 1; o < 64; o <<= 1) v += __shfl_xor(v, o);
;     return v;
; template <bool POST, bool PRE>
; __device__ __forceinline__ void row_core(const Params& P, const RowCfg& c, LAS float* vA, LAS float* vB, LAS float* vP, const bf16_t* RAW, const float* SSQ, bf16_t* H, int row, int lane, f32x4 (&v)[8]) {
;     ...
;     if (PRE) {
;         float s2 = 0.f;
; #pragma unroll
;         for (int j = 0; j < 8; ++j) s2 += (v[j][0] * v[j][0] + v[j][1] * v[j][1]) + (v[j][2] * v[j][2] + v[j][3] * v[j][3]);
;         s2 = wave_sum(s2);
;         const float rstd2 = rsqrtf(s2 * (1.0f / DM) + EPS);
;         u32x2* hs = (u32x2*)(H + (size_t)row * DM) + lane;
; #pragma unroll
;         for (int j = 0; j < 8; ++j) { const f32x4 a = *(const LAS f32x4*)(vA + j * 256 + lane * 4), b = *(const LAS f32x4*)(vB + j * 256 + lane * 4);
;             v[j] = v[j] * rstd2 * a + b; u32x2 w; w.x = cvt_pk_bf16(v[j][0], v[j][1]); w.y = cvt_pk_bf16(v[j][2], v[j][3]); hs[64 * j] = w; }
	v_pk_fma_f32 v[30:31], v[90:91], v[96:97], v[30:31]
	v_pk_fma_f32 v[28:29], v[88:89], v[100:101], v[28:29]
	global_store_dwordx4 v[98:99], v[28:31], off nt
	global_load_dwordx2 v[86:87], v[86:87], off offset:3584
	v_mov_b32_e32 v90, v9
	v_mov_b32_e32 v98, v11
	v_mov_b32_e32 v91, v5
	v_mov_b32_e32 v99, v7
	v_mov_b32_e32 v88, v8
	v_mov_b32_e32 v96, v10
	v_mov_b32_e32 v89, v4
	v_mov_b32_e32 v97, v6
	v_pk_mul_f32 v[90:91], v[90:91], v[90:91]
	v_pk_mul_f32 v[98:99], v[98:99], v[98:99]
	v_pk_fma_f32 v[88:89], v[88:89], v[88:89], v[90:91]
	v_pk_fma_f32 v[90:91], v[96:97], v[96:97], v[98:99]
	v_pk_mul_f32 v[96:97], v[16:17], v[16:17]
	v_pk_add_f32 v[88:89], v[88:89], v[90:91]
	v_pk_mul_f32 v[90:91], v[18:19], v[18:19]
	v_pk_add_f32 v[88:89], v[88:89], v[88:89] op_sel:[0,1] op_sel_hi:[1,0]
	v_pk_mov_b32 v[98:99], v[96:97], v[90:91] op_sel:[1,0]
	v_mov_b32_e32 v97, v91
	v_pk_add_f32 v[90:91], v[98:99], v[96:97]
	v_mul_f32_e32 v96, v13, v13
	v_mul_f32_e32 v98, v15, v15
	v_pk_add_f32 v[90:91], v[90:91], v[90:91] op_sel:[0,1] op_sel_hi:[1,0]
	v_pk_fma_f32 v[96:97], v[12:13], v[12:13], v[96:97] op_sel_hi:[1,1,0]
	v_pk_fma_f32 v[98:99], v[14:15], v[14:15], v[98:99] op_sel_hi:[1,1,0]
	v_mul_f32_e32 v89, v24, v24
	v_mul_f32_e32 v91, v25, v25
	v_mul_f32_e32 v97, v26, v26
	v_mul_f32_e32 v99, v27, v27
	v_pk_add_f32 v[88:89], v[88:89], v[90:91]
	v_pk_add_f32 v[90:91], v[96:97], v[98:99]
	v_pk_mul_f32 v[96:97], v[20:21], v[20:21]
	v_pk_add_f32 v[88:89], v[88:89], v[90:91]
	v_pk_mul_f32 v[90:91], v[22:23], v[22:23]
	v_pk_add_f32 v[88:89], v[88:89], v[88:89] op_sel:[0,1] op_sel_hi:[1,0]
	v_pk_mov_b32 v[98:99], v[96:97], v[90:91] op_sel:[1,0]
	v_mov_b32_e32 v97, v91
	v_pk_add_f32 v[90:91], v[98:99], v[96:97]
	v_mul_f32_e32 v96, v29, v29
	v_mul_f32_e32 v98, v31, v31
	v_pk_add_f32 v[90:91], v[90:91], v[90:91] op_sel:[0,1] op_sel_hi:[1,0]
	v_pk_fma_f32 v[96:97], v[28:29], v[28:29], v[96:97] op_sel_hi:[1,1,0]
	v_pk_fma_f32 v[98:99], v[30:31], v[30:31], v[98:99] op_sel_hi:[1,1,0]
	s_waitcnt vmcnt(0)
	v_lshlrev_b32_e32 v100, 16, v86
	v_and_b32_e32 v101, 0xffff0000, v86
	v_lshlrev_b32_e32 v86, 16, v87
	v_and_b32_e32 v87, 0xffff0000, v87
	v_pk_mul_f32 v[100:101], v[84:85], v[100:101] op_sel_hi:[0,1]
	v_pk_mul_f32 v[84:85], v[84:85], v[86:87] op_sel_hi:[0,1]
	s_waitcnt lgkmcnt(0)
	v_pk_fma_f32 v[182:183], v[94:95], v[84:85], v[2:3]
	v_pk_fma_f32 v[180:181], v[92:93], v[100:101], v[0:1]
	v_mul_f32_e32 v97, v182, v182
	v_mul_f32_e32 v89, v180, v180
	v_mul_f32_e32 v91, v181, v181
	v_mul_f32_e32 v99, v183, v183
	v_pk_add_f32 v[0:1], v[88:89], v[90:91]
	v_pk_add_f32 v[2:3], v[96:97], v[98:99]
	v_lshl_add_u64 v[86:87], v[82:83], 0, s[36:37]
	v_pk_add_f32 v[0:1], v[0:1], v[2:3]
	s_nop 0
	v_add_f32_e32 v0, v0, v1
	s_nop 1
	v_add_f32_dpp v0, v0, v0 quad_perm:[1,0,3,2] row_mask:0xf bank_mask:0xf
	s_nop 1
	v_add_f32_dpp v0, v0, v0 quad_perm:[2,3,0,1] row_mask:0xf bank_mask:0xf
	s_nop 1
	v_add_f32_dpp v0, v0, v0 row_half_mirror row_mask:0xf bank_mask:0xf
	s_nop 1
	v_add_f32_dpp v0, v0, v0 row_mirror row_mask:0xf bank_mask:0xf
	ds_bpermute_b32 v1, v110, v0
	s_waitcnt lgkmcnt(0)
	v_add_f32_e32 v0, v0, v1
	ds_bpermute_b32 v1, v111, v0
	s_waitcnt lgkmcnt(0)
	v_add_f32_e32 v0, v0, v1
	v_fmamk_f32 v0, v0, 0x3a000000, v178
	v_mul_f32_e32 v1, 0x4b800000, v0
	v_cmp_gt_f32_e32 vcc, s17, v0
	s_nop 1
	v_cndmask_b32_e32 v0, v0, v1, vcc
	v_rsq_f32_e32 v88, v0
	ds_read_b128 v[0:3], v112
	ds_read_b128 v[82:85], v112 offset:8192
	global_store_dwordx4 v[86:87], v[180:183], off nt
	v_mul_f32_e32 v86, 0x45800000, v88
	v_cndmask_b32_e32 v184, v88, v86, vcc
	v_pk_mul_f32 v[86:87], v[8:9], v[184:185] op_sel_hi:[1,0]
	v_pk_mul_f32 v[8:9], v[10:11], v[184:185] op_sel_hi:[1,0]
	s_waitcnt lgkmcnt(0)
	v_pk_fma_f32 v[10:11], v[0:1], v[86:87], v[82:83]
	v_pk_fma_f32 v[8:9], v[2:3], v[8:9], v[84:85]
	v_cvt_pk_bf16_f32 v86, v10, v11
	v_pk_mul_f32 v[4:5], v[4:5], v[184:185] op_sel_hi:[1,0]
	v_cvt_pk_bf16_f32 v87, v8, v9
	ds_read_b128 v[0:3], v112 offset:1024
	ds_read_b128 v[82:85], v112 offset:9216
	v_pk_mul_f32 v[6:7], v[6:7], v[184:185] op_sel_hi:[1,0]
	global_store_dwordx2 v[186:187], v[86:87], off
	v_pk_mul_f32 v[16:17], v[16:17], v[184:185] op_sel_hi:[1,0]
	v_pk_mul_f32 v[18:19], v[18:19], v[184:185] op_sel_hi:[1,0]
	s_waitcnt lgkmcnt(0)
	v_pk_fma_f32 v[102:103], v[2:3], v[6:7], v[84:85]
	v_pk_fma_f32 v[104:105], v[0:1], v[4:5], v[82:83]
	v_pk_mul_f32 v[12:13], v[12:13], v[184:185] op_sel_hi:[1,0]
	v_cvt_pk_bf16_f32 v82, v104, v105
	v_cvt_pk_bf16_f32 v83, v102, v103
	ds_read_b128 v[0:3], v112 offset:2048
	ds_read_b128 v[4:7], v112 offset:10240
	global_store_dwordx2 v[186:187], v[82:83], off offset:512
	v_pk_mul_f32 v[14:15], v[14:15], v[184:185] op_sel_hi:[1,0]
	s_waitcnt lgkmcnt(0)
	v_pk_fma_f32 v[96:97], v[2:3], v[18:19], v[6:7]
	v_pk_fma_f32 v[100:101], v[0:1], v[16:17], v[4:5]
	v_pk_mul_f32 v[18:19], v[182:183], v[184:185] op_sel_hi:[1,0]
	v_cvt_pk_bf16_f32 v16, v100, v101
	v_cvt_pk_bf16_f32 v17, v96, v97
	ds_read_b128 v[0:3], v112 offset:3072
	ds_read_b128 v[4:7], v112 offset:11264
	global_store_dwordx2 v[186:187], v[16:17], off offset:1024
	v_pk_mul_f32 v[16:17], v[26:27], v[184:185] op_sel_hi:[1,0]
	s_waitcnt lgkmcnt(0)
	v_pk_fma_f32 v[94:95], v[2:3], v[14:15], v[6:7]
	v_pk_fma_f32 v[98:99], v[0:1], v[12:13], v[4:5]
	v_pk_mul_f32 v[14:15], v[24:25], v[184:185] op_sel_hi:[1,0]
	v_cvt_pk_bf16_f32 v12, v98, v99
	v_cvt_pk_bf16_f32 v13, v94, v95
	ds_read_b128 v[0:3], v112 offset:4096
	ds_read_b128 v[4:7], v112 offset:12288
	global_store_dwordx2 v[186:187], v[12:13], off offset:1536
	s_waitcnt lgkmcnt(0)
	v_pk_fma_f32 v[88:89], v[2:3], v[16:17], v[6:7]
	v_pk_fma_f32 v[92:93], v[0:1], v[14:15], v[4:5]
	v_pk_mul_f32 v[14:15], v[20:21], v[184:185] op_sel_hi:[1,0]
	v_cvt_pk_bf16_f32 v12, v92, v93
	v_cvt_pk_bf16_f32 v13, v88, v89
	ds_read_b128 v[0:3], v112 offset:5120
	ds_read_b128 v[4:7], v112 offset:13312
	v_pk_mul_f32 v[16:17], v[22:23], v[184:185] op_sel_hi:[1,0]
	global_store_dwordx2 v[186:187], v[12:13], off offset:2048
	s_waitcnt lgkmcnt(0)
	v_pk_fma_f32 v[86:87], v[16:17], v[2:3], v[6:7]
	v_pk_fma_f32 v[90:91], v[14:15], v[0:1], v[4:5]
	v_pk_mul_f32 v[6:7], v[28:29], v[184:185] op_sel_hi:[1,0]
	v_cvt_pk_bf16_f32 v0, v90, v91
	v_cvt_pk_bf16_f32 v1, v86, v87
	ds_read_b128 v[2:5], v112 offset:6144
	ds_read_b128 v[12:15], v112 offset:14336
	v_pk_mul_f32 v[16:17], v[30:31], v[184:185] op_sel_hi:[1,0]
	global_store_dwordx2 v[186:187], v[0:1], off offset:2560
	s_waitcnt lgkmcnt(0)
	v_pk_fma_f32 v[0:1], v[16:17], v[4:5], v[14:15]
	v_pk_fma_f32 v[84:85], v[6:7], v[2:3], v[12:13]
	v_pk_mul_f32 v[16:17], v[180:181], v[184:185] op_sel_hi:[1,0]
	v_cvt_pk_bf16_f32 v6, v84, v85
	v_cvt_pk_bf16_f32 v7, v0, v1
	ds_read_b128 v[2:5], v112 offset:7168
	ds_read_b128 v[12:15], v112 offset:15360
	global_store_dwordx2 v[186:187], v[6:7], off offset:3072
	s_waitcnt lgkmcnt(0)
	v_pk_fma_f32 v[82:83], v[18:19], v[4:5], v[14:15]
	v_pk_fma_f32 v[2:3], v[16:17], v[2:3], v[12:13]
	s_nop 0
	v_cvt_pk_bf16_f32 v4, v2, v3
	v_cvt_pk_bf16_f32 v5, v82, v83
	global_store_dwordx2 v[186:187], v[4:5], off offset:3584

; __device__ __forceinline__ unsigned pk2(float lo, float hi) { return f2bf(lo) | (f2bf(hi) << 16); }
; __device__ __forceinline__ float siluf_(float x) { return x * __builtin_amdgcn_rcpf(1.0f + __expf(-x)); }
; __device__ __forceinline__ void gla_finalize(const Ctx& F) {
;     ...
;     for (int row = gw; row < SEQ; row += NGW) {
;         f32x4 o[8]; const u32x4* op0 = (const u32x4*)(O + ((size_t)(lane * 2) * SEQ + row) * 16); const u32x4* op1 = (const u32x4*)(O + ((size_t)(lane * 2 + 1) * SEQ + row) * 16); float ss = 0.f;
;         const u32x4 ob[4] = {op0[0], op0[1], op1[0], op1[1]};
; #pragma unroll
;         for (int i = 0; i < 8; ++i) { const u32x4 q4 = ob[i >> 1]; const unsigned w0 = (i & 1) ? q4.z : q4.x, w1 = (i & 1) ? q4.w : q4.y;
;             o[i] = (f32x4){__uint_as_float(w0 << 16), __uint_as_float(w0 & 0xffff0000u), __uint_as_float(w1 << 16), __uint_as_float(w1 & 0xffff0000u)}; ss += (o[i][0] * o[i][0] + o[i][1] * o[i][1]) + (o[i][2] * o[i][2] + o[i][3] * o[i][3]); }
;         ss += __shfl_xor(ss, 1); ss += __shfl_xor(ss, 2); ss += __shfl_xor(ss, 4); ss += __shfl_xor(ss, 8);
;         const float rstd = rsqrtf(ss * (1.0f / 512.0f) + EPS);
;         const u32x4* rp = (const u32x4*)(Y1 + (size_t)row * 6144 + 4096 + lane * 32); u32x4* cp = (u32x4*)(CAT + (size_t)row * 2048 + lane * 32);
; #pragma unroll
;         for (int i = 0; i < 4; ++i) { const u32x4 rv = rp[i]; const unsigned rr[4] = {rv.x, rv.y, rv.z, rv.w}; unsigned ov[4];
; #pragma unroll
;             for (int j = 0; j < 4; ++j) { const int e = i * 8 + j * 2; const float r0 = __uint_as_float(rr[j] << 16), r1 = __uint_as_float(rr[j] & 0xffff0000u);
;                 const float x0 = o[e >> 2][e & 3], x1 = o[(e + 1) >> 2][(e + 1) & 3];
;                 ov[j] = pk2(x0 * rstd * P.in[36][d0 + e] * siluf_(r0), x1 * rstd * P.in[36][d0 + e + 1] * siluf_(r1)); }
.LBB0_1904:
	v_lshl_add_u64 v[20:21], s[92:93], 0, v[18:19]
	v_lshl_add_u64 v[8:9], s[92:93], 0, v[16:17]
	v_add_co_u32_e32 v54, vcc, 0xac00000, v20
	v_add_co_u32_e64 v58, s[0:1], s7, v8
	v_lshl_add_u64 v[10:11], s[92:93], 0, v[14:15]
	s_nop 0
	v_addc_co_u32_e64 v59, s[0:1], 0, v9, s[0:1]
	v_addc_co_u32_e32 v55, vcc, 0, v21, vcc
	v_lshl_add_u64 v[28:29], v[20:21], 0, s[16:17]
	v_lshl_add_u64 v[52:53], v[20:21], 0, s[18:19]
	v_add_co_u32_e64 v22, s[0:1], s23, v10
	v_add_co_u32_e32 v20, vcc, 0xac80000, v20
	v_mov_b32_e32 v0, v164
	v_mov_b32_e32 v1, v165
	v_mov_b32_e32 v2, v166
	v_mov_b32_e32 v3, v167
	v_mov_b32_e32 v4, v160
	v_mov_b32_e32 v5, v161
	v_mov_b32_e32 v6, v162
	v_mov_b32_e32 v7, v163
	v_lshl_add_u64 v[56:57], v[8:9], 0, s[20:21]
	v_addc_co_u32_e64 v23, s[0:1], 0, v11, s[0:1]
	global_load_dwordx4 v[24:27], v[28:29], off offset:16
	global_load_dwordx4 v[44:47], v[52:53], off offset:16
	global_load_dwordx4 v[30:33], v[58:59], off
	global_load_dwordx4 v[34:37], v[56:57], off offset:16
	global_load_dwordx4 v[48:51], v[56:57], off offset:32
	global_load_dwordx4 v[8:11], v[56:57], off offset:48
	v_addc_co_u32_e32 v21, vcc, 0, v21, vcc
	global_load_dwordx4 v[52:55], v[54:55], off
	s_add_i32 s6, s6, s8
	global_load_dwordx4 v[56:59], v[20:21], off
	v_lshl_add_u64 v[14:15], v[14:15], 0, s[10:11]
	v_lshl_add_u64 v[16:17], v[16:17], 0, s[12:13]
	v_lshl_add_u64 v[18:19], v[18:19], 0, s[14:15]
	s_cmpk_lt_i32 s6, 0x4000
	s_waitcnt vmcnt(9)
	v_mov_b32_e32 v62, v0
	s_waitcnt vmcnt(8)
	v_mov_b32_e32 v60, v4
	s_waitcnt vmcnt(7)
	v_and_b32_e32 v70, 0xffff0000, v26
	s_waitcnt vmcnt(6)
	v_lshlrev_b32_e32 v4, 16, v44
	v_and_b32_e32 v0, 0xffff0000, v44
	v_lshlrev_b32_e32 v28, 16, v45
	s_waitcnt vmcnt(5)
	v_and_b32_e32 v75, 0xffff0000, v31
	v_lshlrev_b32_e32 v76, 16, v32
	v_lshlrev_b32_e32 v20, 16, v46
	s_waitcnt vmcnt(1)
	v_lshlrev_b32_e32 v93, 16, v53
	v_lshlrev_b32_e32 v92, 16, v52
	v_and_b32_e32 v53, 0xffff0000, v53
	v_and_b32_e32 v52, 0xffff0000, v52
	v_lshlrev_b32_e32 v95, 16, v55
	v_lshlrev_b32_e32 v94, 16, v54
	v_and_b32_e32 v55, 0xffff0000, v55
	v_and_b32_e32 v54, 0xffff0000, v54
	v_lshlrev_b32_e32 v65, 16, v25
	v_lshlrev_b32_e32 v64, 16, v24
	v_and_b32_e32 v67, 0xffff0000, v25
	v_and_b32_e32 v66, 0xffff0000, v24
	v_lshlrev_b32_e32 v68, 16, v26
	v_lshlrev_b32_e32 v72, 16, v27
	v_and_b32_e32 v29, 0xffff0000, v45
	v_lshlrev_b32_e32 v81, 16, v35
	v_lshlrev_b32_e32 v80, 16, v34
	v_and_b32_e32 v83, 0xffff0000, v35
	v_and_b32_e32 v82, 0xffff0000, v34
	v_lshlrev_b32_e32 v85, 16, v37
	v_lshlrev_b32_e32 v84, 16, v36
	v_and_b32_e32 v87, 0xffff0000, v37
	v_and_b32_e32 v86, 0xffff0000, v36
	v_lshlrev_b32_e32 v35, 16, v51
	v_lshlrev_b32_e32 v34, 16, v50
	v_and_b32_e32 v37, 0xffff0000, v51
	v_and_b32_e32 v36, 0xffff0000, v50
	v_lshlrev_b32_e32 v21, 16, v47
	v_and_b32_e32 v25, 0xffff0000, v47
	v_and_b32_e32 v24, 0xffff0000, v46
	v_mul_f32_e32 v51, v70, v70
	v_mul_f32_e32 v89, v4, v4
	v_mul_f32_e32 v91, v0, v0
	v_mul_f32_e32 v50, v28, v28
	v_mul_f32_e32 v104, 0xbfb8aa3b, v75
	v_mul_f32_e32 v112, 0xbfb8aa3b, v76
	v_mov_b32_e32 v88, v20
	v_mov_b32_e32 v90, v20
	s_waitcnt vmcnt(0)
	v_lshlrev_b32_e32 v101, 16, v59
	v_lshlrev_b32_e32 v100, 16, v58
	v_and_b32_e32 v59, 0xffff0000, v59
	v_and_b32_e32 v58, 0xffff0000, v58
	v_mov_b32_e32 v106, v52
	v_mov_b32_e32 v107, v54
	v_mov_b32_e32 v110, v53
	v_mov_b32_e32 v111, v55
	v_and_b32_e32 v73, 0xffff0000, v27
	v_lshlrev_b32_e32 v45, 16, v31
	v_lshlrev_b32_e32 v44, 16, v30
	v_and_b32_e32 v74, 0xffff0000, v30
	v_lshlrev_b32_e32 v77, 16, v33
	v_and_b32_e32 v79, 0xffff0000, v33
	v_and_b32_e32 v78, 0xffff0000, v32
	v_lshlrev_b32_e32 v31, 16, v49
	v_lshlrev_b32_e32 v30, 16, v48
	v_and_b32_e32 v33, 0xffff0000, v49
	v_and_b32_e32 v32, 0xffff0000, v48
	v_mul_f32_e32 v49, v68, v68
	v_mul_f32_e32 v48, v72, v72
	v_pk_mul_f32 v[96:97], v[24:25], v[24:25]
	v_pk_mul_f32 v[98:99], v[20:21], v[20:21]
	v_pk_fma_f32 v[102:103], v[28:29], v[28:29], v[50:51] op_sel_hi:[1,1,0]
	v_exp_f32_e32 v132, v104
	v_mov_b32_e32 v104, v92
	v_mov_b32_e32 v105, v94
	v_mov_b32_e32 v108, v93
	v_mov_b32_e32 v109, v95
	v_exp_f32_e32 v133, v112
	v_lshlrev_b32_e32 v112, 16, v56
	v_pk_add_f32 v[88:89], v[88:89], v[90:91]
	v_pk_mul_f32 v[90:91], v[58:59], v[58:59]
	v_pk_mul_f32 v[106:107], v[106:107], v[106:107]
	v_pk_mul_f32 v[110:111], v[110:111], v[110:111]
	v_mov_b32_e32 v69, v72
	v_mov_b32_e32 v71, v73
	v_pk_fma_f32 v[72:73], v[72:73], v[72:73], v[48:49] op_sel_hi:[1,1,0]
	v_mov_b32_e32 v48, v112
	v_mov_b32_e32 v50, v112
	v_mov_b32_e32 v88, v98
	v_mov_b32_e32 v102, v96
	v_pk_fma_f32 v[90:91], v[100:101], v[100:101], v[90:91]
	v_pk_fma_f32 v[104:105], v[104:105], v[104:105], v[106:107]
	v_pk_fma_f32 v[106:107], v[108:109], v[108:109], v[110:111]
	v_pk_mul_f32 v[46:47], v[66:67], v[66:67]
	v_mul_f32_e32 v113, 0xbfb8aa3b, v78
	v_pk_add_f32 v[48:49], v[48:49], v[50:51]
	v_pk_add_f32 v[50:51], v[88:89], v[102:103]
	v_pk_add_f32 v[88:89], v[90:91], v[90:91] op_sel_hi:[0,1]
	v_pk_add_f32 v[90:91], v[104:105], v[106:107]
	v_mul_f32_e32 v114, 0xbfb8aa3b, v77
	v_mul_f32_e32 v115, 0xbfb8aa3b, v79
	v_mul_f32_e32 v116, 0xbfb8aa3b, v80
	v_mul_f32_e32 v117, 0xbfb8aa3b, v82
	v_pk_fma_f32 v[46:47], v[64:65], v[64:65], v[46:47]
	v_exp_f32_e32 v134, v113
	v_lshlrev_b32_e32 v113, 16, v57
	v_and_b32_e32 v57, 0xffff0000, v57
	v_and_b32_e32 v56, 0xffff0000, v56
	v_pk_add_f32 v[90:91], v[90:91], v[90:91] op_sel_hi:[0,1]
	v_exp_f32_e32 v135, v114
	v_exp_f32_e32 v136, v115
	v_exp_f32_e32 v137, v116
	v_exp_f32_e32 v138, v117
	v_pk_add_f32 v[46:47], v[46:47], v[46:47] op_sel_hi:[0,1]
	v_pk_mul_f32 v[114:115], v[56:57], v[56:57]
	v_pk_mul_f32 v[116:117], v[112:113], v[112:113]
; __device__ __forceinline__ unsigned pk2(float lo, float hi) { return f2bf(lo) | (f2bf(hi) << 16); }
; __device__ __forceinline__ float siluf_(float x) { return x * __builtin_amdgcn_rcpf(1.0f + __expf(-x)); }
; __device__ __forceinline__ void gla_finalize(const Ctx& F) {
;     ...
;         ss += __shfl_xor(ss, 1); ss += __shfl_xor(ss, 2); ss += __shfl_xor(ss, 4); ss += __shfl_xor(ss, 8);
;         const float rstd = rsqrtf(ss * (1.0f / 512.0f) + EPS);
;         const u32x4* rp = (const u32x4*)(Y1 + (size_t)row * 6144 + 4096 + lane * 32); u32x4* cp = (u32x4*)(CAT + (size_t)row * 2048 + lane * 32);
; #pragma unroll
;         for (int i = 0; i < 4; ++i) { const u32x4 rv = rp[i]; const unsigned rr[4] = {rv.x, rv.y, rv.z, rv.w}; unsigned ov[4];
; #pragma unroll
;             for (int j = 0; j < 4; ++j) { const int e = i * 8 + j * 2; const float r0 = __uint_as_float(rr[j] << 16), r1 = __uint_as_float(rr[j] & 0xffff0000u);
;                 const float x0 = o[e >> 2][e & 3], x1 = o[(e + 1) >> 2][(e + 1) & 3];
;                 ov[j] = pk2(x0 * rstd * P.in[36][d0 + e] * siluf_(r0), x1 * rstd * P.in[36][d0 + e + 1] * siluf_(r1)); }
;             cp[i] = (u32x4){ov[0], ov[1], ov[2], ov[3]}; }
	v_add_f32_e32 v90, 1.0, v133
	v_mov_b32_e32 v72, v114
	v_mov_b32_e32 v46, v115
	v_mov_b32_e32 v48, v116
	v_rcp_f32_e32 v102, v90
	v_mov_b32_e32 v90, v117
	v_mov_b32_e32 v63, v2
	v_mov_b32_e32 v2, v1
	v_mul_f32_e32 v1, 0xbfb8aa3b, v44
	v_pk_add_f32 v[48:49], v[48:49], v[72:73]
	v_pk_add_f32 v[46:47], v[90:91], v[46:47]
	v_mov_b32_e32 v61, v6
	v_mov_b32_e32 v6, v5
	v_mul_f32_e32 v5, 0xbfb8aa3b, v74
	v_exp_f32_e32 v1, v1
	v_pk_add_f32 v[46:47], v[48:49], v[46:47]
	v_exp_f32_e32 v5, v5
	v_pk_add_f32 v[46:47], v[46:47], v[46:47] op_sel_hi:[0,1]
	v_mov_b32_e32 v88, v99
	v_mov_b32_e32 v46, v97
	v_pk_add_f32 v[46:47], v[88:89], v[46:47]
	v_add_f32_e32 v1, 1.0, v1
	v_pk_add_f32 v[46:47], v[50:51], v[46:47]
	v_add_f32_e32 v5, 1.0, v5
	v_rcp_f32_e32 v72, v1
	v_add_f32_e32 v1, v46, v47
	v_rcp_f32_e32 v98, v5
	s_nop 1
	v_add_f32_dpp v1, v1, v1 quad_perm:[1,0,3,2] row_mask:0xf bank_mask:0xf
	v_mul_f32_e32 v43, 0xbfb8aa3b, v45
	v_mul_f32_e32 v118, 0xbfb8aa3b, v81
	v_mul_f32_e32 v119, 0xbfb8aa3b, v83
	v_mul_f32_e32 v120, 0xbfb8aa3b, v84
	s_nop 1
	v_add_f32_dpp v1, v1, v1 quad_perm:[2,3,0,1] row_mask:0xf bank_mask:0xf
	v_mul_f32_e32 v122, 0xbfb8aa3b, v85
	v_exp_f32_e32 v43, v43
	v_exp_f32_e32 v118, v118
	v_exp_f32_e32 v119, v119
	s_nop 1
	v_add_f32_dpp v1, v1, v1 row_half_mirror row_mask:0xf bank_mask:0xf
	v_exp_f32_e32 v120, v120
	v_exp_f32_e32 v122, v122
	v_add_f32_e32 v43, 1.0, v43
	v_add_f32_e32 v103, 1.0, v134
	s_nop 1
	v_add_f32_dpp v1, v1, v1 row_mirror row_mask:0xf bank_mask:0xf
	v_add_f32_e32 v105, 1.0, v135
	v_add_f32_e32 v106, 1.0, v136
	v_add_f32_e32 v107, 1.0, v137
	v_add_f32_e32 v109, 1.0, v118
	v_fmamk_f32 v1, v1, 0x3b000000, v42
	v_mul_f32_e32 v5, 0x4b800000, v1
	v_cmp_gt_f32_e32 vcc, s9, v1
	v_add_f32_e32 v110, 1.0, v119
	v_add_f32_e32 v111, 1.0, v120
	v_cndmask_b32_e32 v1, v1, v5, vcc
	v_add_f32_e32 v115, 1.0, v122
	v_rsq_f32_e32 v1, v1
	v_rcp_f32_e32 v73, v43
	v_rcp_f32_e32 v104, v103
	v_rcp_f32_e32 v103, v105
	v_rcp_f32_e32 v105, v106
	v_rcp_f32_e32 v106, v107
	v_rcp_f32_e32 v107, v109
	v_rcp_f32_e32 v109, v110
	v_rcp_f32_e32 v110, v111
	v_rcp_f32_e32 v111, v115
	v_add_f32_e32 v96, 1.0, v132
	v_rcp_f32_e32 v99, v96
	v_mul_f32_e32 v5, 0x45800000, v1
	v_pk_mul_f32 v[44:45], v[72:73], v[44:45]
	v_pk_mul_f32 v[72:73], v[102:103], v[76:77]
	v_pk_mul_f32 v[76:77], v[106:107], v[80:81]
	v_pk_mul_f32 v[80:81], v[110:111], v[84:85]
	v_cndmask_b32_e32 v84, v1, v5, vcc
	v_pk_mul_f32 v[46:47], v[84:85], v[92:93] op_sel_hi:[0,1]
	v_pk_mul_f32 v[50:51], v[84:85], v[52:53] op_sel_hi:[0,1]
	v_pk_mul_f32 v[52:53], v[84:85], v[94:95] op_sel_hi:[0,1]
	v_pk_mul_f32 v[54:55], v[84:85], v[54:55] op_sel_hi:[0,1]
	v_pk_mul_f32 v[48:49], v[98:99], v[74:75]
	v_pk_mul_f32 v[74:75], v[104:105], v[78:79]
	v_pk_mul_f32 v[46:47], v[60:61], v[46:47]
	v_pk_mul_f32 v[6:7], v[6:7], v[50:51]
	v_pk_mul_f32 v[50:51], v[62:63], v[52:53]
	v_pk_mul_f32 v[2:3], v[2:3], v[54:55]
	v_pk_mul_f32 v[44:45], v[44:45], v[46:47]
	v_pk_mul_f32 v[6:7], v[48:49], v[6:7]
	v_pk_mul_f32 v[46:47], v[72:73], v[50:51]
	v_pk_mul_f32 v[2:3], v[74:75], v[2:3]
	v_bfe_u32 v43, v7, 16, 1
	v_bfe_u32 v1, v3, 16, 1
	v_bfe_u32 v5, v2, 16, 1
	v_bfe_u32 v49, v44, 16, 1
	v_bfe_u32 v50, v45, 16, 1
	v_bfe_u32 v51, v46, 16, 1
	v_bfe_u32 v52, v47, 16, 1
	v_bfe_u32 v48, v6, 16, 1
	v_add3_u32 v7, v7, v43, s22
	v_add3_u32 v2, v2, v5, s22
	v_add3_u32 v1, v3, v1, s22
	v_add3_u32 v3, v47, v52, s22
	v_add3_u32 v5, v46, v51, s22
	v_add3_u32 v43, v45, v50, s22
	v_add3_u32 v44, v44, v49, s22
	v_add3_u32 v6, v6, v48, s22
	v_lshrrev_b32_e32 v44, 16, v44
	v_lshrrev_b32_e32 v43, 16, v43
	v_lshrrev_b32_e32 v5, 16, v5
	v_lshrrev_b32_e32 v3, 16, v3
	v_and_or_b32 v47, v1, s3, v3
	v_and_or_b32 v46, v2, s3, v5
	v_and_or_b32 v45, v7, s3, v43
	v_and_or_b32 v44, v6, s3, v44
	global_store_dwordx4 v[22:23], v[44:47], off
	s_nop 1
	v_mov_b32_e32 v44, v168
	v_mov_b32_e32 v45, v169
	v_mov_b32_e32 v46, v170
	v_mov_b32_e32 v47, v171
	s_nop 0
	v_mov_b32_e32 v48, v172
	v_mov_b32_e32 v49, v173
	v_mov_b32_e32 v50, v174
	v_mov_b32_e32 v51, v175
	v_mul_f32_e32 v121, 0xbfb8aa3b, v86
	v_mul_f32_e32 v123, 0xbfb8aa3b, v87
	v_exp_f32_e32 v121, v121
	v_exp_f32_e32 v123, v123
	v_add_f32_e32 v108, 1.0, v138
	v_rcp_f32_e32 v108, v108
	v_add_f32_e32 v114, 1.0, v121
	v_add_f32_e32 v116, 1.0, v123
	v_rcp_f32_e32 v114, v114
	v_rcp_f32_e32 v115, v116
	v_pk_mul_f32 v[64:65], v[84:85], v[64:65] op_sel_hi:[0,1]
	v_pk_mul_f32 v[68:69], v[84:85], v[68:69] op_sel_hi:[0,1]
	v_pk_mul_f32 v[66:67], v[84:85], v[66:67] op_sel_hi:[0,1]
	v_pk_mul_f32 v[70:71], v[84:85], v[70:71] op_sel_hi:[0,1]
	v_pk_mul_f32 v[78:79], v[108:109], v[82:83]
	v_pk_mul_f32 v[82:83], v[114:115], v[86:87]
	v_mul_f32_e32 v124, 0xbfb8aa3b, v30
	v_mul_f32_e32 v125, 0xbfb8aa3b, v32
	v_mul_f32_e32 v126, 0xbfb8aa3b, v31
	v_mul_f32_e32 v127, 0xbfb8aa3b, v33
	v_mul_f32_e32 v128, 0xbfb8aa3b, v34
	v_mul_f32_e32 v129, 0xbfb8aa3b, v36
	v_mul_f32_e32 v130, 0xbfb8aa3b, v35
	v_mul_f32_e32 v131, 0xbfb8aa3b, v37
	v_exp_f32_e32 v124, v124
	v_exp_f32_e32 v125, v125
	v_exp_f32_e32 v126, v126
	v_exp_f32_e32 v127, v127
	v_exp_f32_e32 v128, v128
	v_exp_f32_e32 v129, v129
	v_exp_f32_e32 v130, v130
	v_exp_f32_e32 v131, v131
	v_add_f32_e32 v118, 1.0, v124
	v_add_f32_e32 v119, 1.0, v125
	v_add_f32_e32 v120, 1.0, v126
	v_add_f32_e32 v121, 1.0, v127
	v_add_f32_e32 v122, 1.0, v128
	v_add_f32_e32 v123, 1.0, v129
	v_add_f32_e32 v124, 1.0, v130
	v_rcp_f32_e32 v54, v123
	v_rcp_f32_e32 v53, v124
	v_lshlrev_b32_e32 v27, 16, v9
	v_lshlrev_b32_e32 v26, 16, v8
	v_pk_mul_f32 v[20:21], v[84:85], v[20:21] op_sel_hi:[0,1]
	v_pk_mul_f32 v[24:25], v[84:85], v[24:25] op_sel_hi:[0,1]
	v_mov_b32_e32 v2, v44
	v_mov_b32_e32 v3, v46
; __device__ __forceinline__ unsigned pk2(float lo, float hi) { return f2bf(lo) | (f2bf(hi) << 16); }
; __device__ __forceinline__ float siluf_(float x) { return x * __builtin_amdgcn_rcpf(1.0f + __expf(-x)); }
; __device__ __forceinline__ void gla_finalize(const Ctx& F) {
;     ...
;         for (int i = 0; i < 4; ++i) { const u32x4 rv = rp[i]; const unsigned rr[4] = {rv.x, rv.y, rv.z, rv.w}; unsigned ov[4];
; #pragma unroll
;             for (int j = 0; j < 4; ++j) { const int e = i * 8 + j * 2; const float r0 = __uint_as_float(rr[j] << 16), r1 = __uint_as_float(rr[j] & 0xffff0000u);
;                 const float x0 = o[e >> 2][e & 3], x1 = o[(e + 1) >> 2][(e + 1) & 3];
;                 ov[j] = pk2(x0 * rstd * P.in[36][d0 + e] * siluf_(r0), x1 * rstd * P.in[36][d0 + e + 1] * siluf_(r1)); }
;             cp[i] = (u32x4){ov[0], ov[1], ov[2], ov[3]}; }
	v_mov_b32_e32 v6, v48
	v_mov_b32_e32 v7, v50
	v_mov_b32_e32 v46, v45
	v_mov_b32_e32 v50, v49
	v_pk_mul_f32 v[2:3], v[2:3], v[64:65]
	v_pk_mul_f32 v[6:7], v[6:7], v[68:69]
	v_pk_mul_f32 v[44:45], v[46:47], v[66:67]
	v_pk_mul_f32 v[46:47], v[50:51], v[70:71]
	v_pk_mul_f32 v[2:3], v[76:77], v[2:3]
	v_pk_mul_f32 v[6:7], v[80:81], v[6:7]
	v_pk_mul_f32 v[44:45], v[78:79], v[44:45]
	v_pk_mul_f32 v[46:47], v[82:83], v[46:47]
	v_bfe_u32 v49, v2, 16, 1
	v_bfe_u32 v50, v3, 16, 1
	v_bfe_u32 v51, v6, 16, 1
	v_bfe_u32 v52, v7, 16, 1
	v_bfe_u32 v1, v47, 16, 1
	v_bfe_u32 v5, v46, 16, 1
	v_bfe_u32 v43, v45, 16, 1
	v_bfe_u32 v48, v44, 16, 1
	v_add3_u32 v7, v7, v52, s22
	v_add3_u32 v6, v6, v51, s22
	v_add3_u32 v3, v3, v50, s22
	v_add3_u32 v2, v2, v49, s22
	v_add3_u32 v44, v44, v48, s22
	v_add3_u32 v43, v45, v43, s22
	v_add3_u32 v5, v46, v5, s22
	v_add3_u32 v1, v47, v1, s22
	v_lshrrev_b32_e32 v2, 16, v2
	v_lshrrev_b32_e32 v3, 16, v3
	v_lshrrev_b32_e32 v6, 16, v6
	v_lshrrev_b32_e32 v7, 16, v7
	v_and_or_b32 v47, v1, s3, v7
	v_and_or_b32 v46, v5, s3, v6
	v_and_or_b32 v45, v43, s3, v3
	v_and_or_b32 v44, v44, s3, v2
	global_store_dwordx4 v[22:23], v[44:47], off offset:16
	s_nop 1
	v_mov_b32_e32 v44, v176
	v_mov_b32_e32 v45, v177
	v_mov_b32_e32 v46, v178
	v_mov_b32_e32 v47, v179
	s_nop 0
	v_mov_b32_e32 v48, v180
	v_mov_b32_e32 v49, v181
	v_mov_b32_e32 v50, v182
	v_mov_b32_e32 v51, v183
	v_add_f32_e32 v1, 1.0, v131
	v_rcp_f32_e32 v2, v118
	v_rcp_f32_e32 v6, v119
	v_rcp_f32_e32 v3, v120
	v_rcp_f32_e32 v7, v121
	v_rcp_f32_e32 v52, v122
	v_rcp_f32_e32 v55, v1
	v_pk_mul_f32 v[2:3], v[2:3], v[30:31]
	v_pk_mul_f32 v[6:7], v[6:7], v[32:33]
	v_pk_mul_f32 v[30:31], v[52:53], v[34:35]
	v_pk_mul_f32 v[32:33], v[54:55], v[36:37]
	v_pk_mul_f32 v[34:35], v[84:85], v[112:113] op_sel_hi:[0,1]
	v_pk_mul_f32 v[36:37], v[84:85], v[56:57] op_sel_hi:[0,1]
	v_pk_mul_f32 v[52:53], v[84:85], v[100:101] op_sel_hi:[0,1]
	v_pk_mul_f32 v[54:55], v[84:85], v[58:59] op_sel_hi:[0,1]
	v_mov_b32_e32 v56, v44
	v_mov_b32_e32 v57, v46
	v_mov_b32_e32 v46, v45
	v_mov_b32_e32 v44, v48
	v_mov_b32_e32 v45, v50
	v_mov_b32_e32 v50, v49
	v_pk_mul_f32 v[34:35], v[34:35], v[56:57]
	v_pk_mul_f32 v[44:45], v[52:53], v[44:45]
	v_pk_mul_f32 v[36:37], v[36:37], v[46:47]
	v_pk_mul_f32 v[46:47], v[54:55], v[50:51]
	v_pk_mul_f32 v[2:3], v[34:35], v[2:3]
	v_pk_mul_f32 v[30:31], v[30:31], v[44:45]
	v_pk_mul_f32 v[6:7], v[36:37], v[6:7]
	v_pk_mul_f32 v[32:33], v[32:33], v[46:47]
	v_bfe_u32 v36, v2, 16, 1
	v_bfe_u32 v37, v3, 16, 1
	v_bfe_u32 v43, v30, 16, 1
	v_bfe_u32 v44, v31, 16, 1
	v_bfe_u32 v1, v33, 16, 1
	v_bfe_u32 v5, v32, 16, 1
	v_bfe_u32 v34, v7, 16, 1
	v_bfe_u32 v35, v6, 16, 1
	v_add3_u32 v31, v31, v44, s22
	v_add3_u32 v30, v30, v43, s22
	v_add3_u32 v3, v3, v37, s22
	v_add3_u32 v2, v2, v36, s22
	v_add3_u32 v6, v6, v35, s22
	v_add3_u32 v7, v7, v34, s22
	v_add3_u32 v5, v32, v5, s22
	v_add3_u32 v1, v33, v1, s22
	v_lshrrev_b32_e32 v2, 16, v2
	v_lshrrev_b32_e32 v3, 16, v3
	v_lshrrev_b32_e32 v30, 16, v30
	v_lshrrev_b32_e32 v31, 16, v31
	v_and_or_b32 v33, v1, s3, v31
	v_and_or_b32 v32, v5, s3, v30
	v_and_or_b32 v31, v7, s3, v3
	v_and_or_b32 v30, v6, s3, v2
	global_store_dwordx4 v[22:23], v[30:33], off offset:32
	s_nop 1
	v_mov_b32_e32 v30, v184
	v_mov_b32_e32 v31, v185
	v_mov_b32_e32 v32, v186
	v_mov_b32_e32 v33, v187
	s_nop 0
	v_mov_b32_e32 v34, v188
	v_mov_b32_e32 v35, v189
	v_mov_b32_e32 v36, v190
	v_mov_b32_e32 v37, v191
	v_and_b32_e32 v3, 0xffff0000, v9
	v_and_b32_e32 v2, 0xffff0000, v8
	v_lshlrev_b32_e32 v7, 16, v11
	v_lshlrev_b32_e32 v6, 16, v10
	v_and_b32_e32 v9, 0xffff0000, v11
	v_and_b32_e32 v8, 0xffff0000, v10
	v_mul_f32_e32 v10, 0xbfb8aa3b, v26
	v_mul_f32_e32 v11, 0xbfb8aa3b, v2
	v_mov_b32_e32 v5, v28
	v_mul_f32_e32 v28, 0xbfb8aa3b, v27
	v_mov_b32_e32 v1, v29
	v_mul_f32_e32 v29, 0xbfb8aa3b, v3
	v_mul_f32_e32 v43, 0xbfb8aa3b, v6
	v_mul_f32_e32 v45, 0xbfb8aa3b, v7
	v_exp_f32_e32 v10, v10
	v_exp_f32_e32 v11, v11
	v_exp_f32_e32 v28, v28
	v_exp_f32_e32 v29, v29
	v_mul_f32_e32 v44, 0xbfb8aa3b, v8
	v_mul_f32_e32 v46, 0xbfb8aa3b, v9
	v_exp_f32_e32 v43, v43
	v_exp_f32_e32 v45, v45
	v_exp_f32_e32 v44, v44
	v_exp_f32_e32 v46, v46
	v_add_f32_e32 v10, 1.0, v10
	v_add_f32_e32 v11, 1.0, v11
	v_add_f32_e32 v47, 1.0, v28
	v_add_f32_e32 v29, 1.0, v29
	v_add_f32_e32 v43, 1.0, v43
	v_add_f32_e32 v45, 1.0, v45
	v_rcp_f32_e32 v10, v10
	v_rcp_f32_e32 v28, v11
	v_rcp_f32_e32 v11, v47
	v_rcp_f32_e32 v29, v29
	v_add_f32_e32 v48, 1.0, v44
	v_add_f32_e32 v49, 1.0, v46
	v_rcp_f32_e32 v44, v43
	v_rcp_f32_e32 v45, v45
	v_rcp_f32_e32 v46, v48
	v_rcp_f32_e32 v47, v49
	v_pk_mul_f32 v[10:11], v[10:11], v[26:27]
	v_pk_mul_f32 v[2:3], v[28:29], v[2:3]
	v_pk_mul_f32 v[4:5], v[84:85], v[4:5] op_sel_hi:[0,1]
	v_pk_mul_f32 v[0:1], v[84:85], v[0:1] op_sel_hi:[0,1]
	v_pk_mul_f32 v[6:7], v[44:45], v[6:7]
	v_pk_mul_f32 v[8:9], v[46:47], v[8:9]
	v_mov_b32_e32 v26, v30
	v_mov_b32_e32 v27, v32
	v_mov_b32_e32 v32, v31
	v_mov_b32_e32 v28, v34
	v_mov_b32_e32 v29, v36
	v_mov_b32_e32 v36, v35
	v_pk_mul_f32 v[4:5], v[4:5], v[26:27]
	v_pk_mul_f32 v[0:1], v[0:1], v[32:33]
	v_pk_mul_f32 v[20:21], v[20:21], v[28:29]
	v_pk_mul_f32 v[24:25], v[24:25], v[36:37]
	v_pk_mul_f32 v[4:5], v[4:5], v[10:11]
	v_pk_mul_f32 v[0:1], v[0:1], v[2:3]
	v_pk_mul_f32 v[2:3], v[6:7], v[20:21]
	v_pk_mul_f32 v[6:7], v[8:9], v[24:25]
	v_bfe_u32 v20, v4, 16, 1
	v_bfe_u32 v21, v5, 16, 1
	v_bfe_u32 v24, v2, 16, 1
	v_bfe_u32 v25, v3, 16, 1
	v_bfe_u32 v8, v7, 16, 1
	v_bfe_u32 v9, v6, 16, 1
	v_bfe_u32 v10, v1, 16, 1
	v_bfe_u32 v11, v0, 16, 1
	v_add3_u32 v3, v3, v25, s22
	v_add3_u32 v2, v2, v24, s22
	v_add3_u32 v5, v5, v21, s22
	v_add3_u32 v4, v4, v20, s22
	v_add3_u32 v0, v0, v11, s22
	v_add3_u32 v1, v1, v10, s22
	v_add3_u32 v6, v6, v9, s22
	v_add3_u32 v7, v7, v8, s22
	v_lshrrev_b32_e32 v4, 16, v4
	v_lshrrev_b32_e32 v5, 16, v5
	v_lshrrev_b32_e32 v2, 16, v2
	v_lshrrev_b32_e32 v3, 16, v3
	v_and_or_b32 v3, v7, s3, v3
	v_and_or_b32 v2, v6, s3, v2
	v_and_or_b32 v1, v1, s3, v5
	v_and_or_b32 v0, v0, s3, v4
	global_store_dwordx4 v[22:23], v[0:3], off offset:48
	s_cbranch_scc1 .LBB0_1904

; #define LAS __attribute__((address_space(3)))
; template <bool POST, bool PRE>
; __device__ __forceinline__ void row_core(const Params& P, const RowCfg& c, LAS float* vA, LAS float* vB, LAS float* vP, const bf16_t* RAW, const float* SSQ, bf16_t* H, int row, int lane, f32x4 (&v)[8]) {
;     ...
;         const u32x2* rs = (const u32x2*)(RAW + (size_t)row * DM) + lane;
;         float s = (lane < 32) ? SSQ[(size_t)row * 32 + lane] : 0.f; s = wave_sum(s);
;         const float rstd = rsqrtf(s * (1.0f / DM) + EPS);
;         f32x4* os = (f32x4*)(P.out + (size_t)row * DM) + lane;
; #pragma unroll
;         for (int j = 0; j < 8; ++j) { const u32x2 rb = rs[64 * j]; const f32x4 r = (f32x4){__uint_as_float(rb.x << 16), __uint_as_float(rb.x & 0xffff0000u), __uint_as_float(rb.y << 16), __uint_as_float(rb.y & 0xffff0000u)};
;             const f32x4 pv = *(const LAS f32x4*)(vP + j * 256 + lane * 4); v[j] += r * rstd * pv; os[64 * j] = v[j]; }
.LBB0_2053:
	s_or_b64 exec, exec, s[0:1]
	v_lshl_add_u64 v[40:41], s[92:93], 0, v[38:39]
	v_add_co_u32_e64 v58, s[0:1], s7, v40
	s_waitcnt vmcnt(0)
	ds_bpermute_b32 v49, v43, v42
	v_addc_co_u32_e64 v59, s[0:1], 0, v41, s[0:1]
	global_load_dwordx2 v[60:61], v[58:59], off
	s_add_i32 s6, s6, s8
	s_waitcnt lgkmcnt(0)
	v_add_f32_e32 v42, v42, v49
	ds_bpermute_b32 v49, v44, v42
	v_lshl_add_u64 v[34:35], v[34:35], 0, s[10:11]
	s_cmpk_lt_i32 s6, 0x4000
	v_lshl_add_u64 v[38:39], v[38:39], 0, s[14:15]
	s_waitcnt lgkmcnt(0)
	v_add_f32_e32 v42, v42, v49
	ds_bpermute_b32 v49, v45, v42
	s_waitcnt lgkmcnt(0)
	v_add_f32_e32 v42, v42, v49
	ds_bpermute_b32 v49, v46, v42
	s_waitcnt lgkmcnt(0)
	v_add_f32_e32 v42, v42, v49
	ds_bpermute_b32 v49, v47, v42
	s_waitcnt lgkmcnt(0)
	v_add_f32_e32 v42, v42, v49
	ds_bpermute_b32 v49, v48, v42
	s_waitcnt lgkmcnt(0)
	v_add_f32_e32 v42, v42, v49
	v_fmamk_f32 v42, v42, 0x3a000000, v33
	v_mul_f32_e32 v49, 0x4b800000, v42
	v_cmp_gt_f32_e64 s[0:1], s3, v42
	s_waitcnt vmcnt(0)
	v_and_b32_e32 v63, 0xffff0000, v60
	v_cndmask_b32_e64 v42, v42, v49, s[0:1]
	v_rsq_f32_e32 v42, v42
	v_add_u32_e32 v49, 0, v32
	ds_read_b128 v[50:53], v49 offset:16384
	ds_read_b128 v[54:57], v49 offset:17408
	v_mul_f32_e32 v62, 0x45800000, v42
	v_cndmask_b32_e64 v42, v42, v62, s[0:1]
	v_lshlrev_b32_e32 v62, 16, v60
	v_lshlrev_b32_e32 v60, 16, v61
	v_and_b32_e32 v61, 0xffff0000, v61
	v_pk_mul_f32 v[62:63], v[42:43], v[62:63] op_sel_hi:[0,1]
	v_pk_mul_f32 v[60:61], v[42:43], v[60:61] op_sel_hi:[0,1]
	s_waitcnt lgkmcnt(1)
	v_pk_fma_f32 v[22:23], v[52:53], v[60:61], v[22:23]
	v_pk_fma_f32 v[20:21], v[50:51], v[62:63], v[20:21]
	global_store_dwordx4 v[36:37], v[20:23], off offset:-4096 nt
	global_load_dwordx2 v[50:51], v[58:59], off offset:512
	s_waitcnt vmcnt(0)
	v_lshlrev_b32_e32 v52, 16, v50
	v_and_b32_e32 v53, 0xffff0000, v50
	v_lshlrev_b32_e32 v50, 16, v51
	v_and_b32_e32 v51, 0xffff0000, v51
	v_pk_mul_f32 v[52:53], v[42:43], v[52:53] op_sel_hi:[0,1]
	v_pk_mul_f32 v[50:51], v[42:43], v[50:51] op_sel_hi:[0,1]
	s_waitcnt lgkmcnt(0)
	v_pk_fma_f32 v[14:15], v[56:57], v[50:51], v[14:15]
	v_pk_fma_f32 v[12:13], v[54:55], v[52:53], v[12:13]
	global_store_dwordx4 v[36:37], v[12:15], off offset:-3072 nt
	global_load_dwordx2 v[60:61], v[58:59], off offset:1024
	ds_read_b128 v[50:53], v49 offset:18432
	ds_read_b128 v[54:57], v49 offset:19456
	s_waitcnt vmcnt(0)
	v_lshlrev_b32_e32 v62, 16, v60
	v_and_b32_e32 v63, 0xffff0000, v60
	v_lshlrev_b32_e32 v60, 16, v61
	v_and_b32_e32 v61, 0xffff0000, v61
	v_pk_mul_f32 v[62:63], v[42:43], v[62:63] op_sel_hi:[0,1]
	v_pk_mul_f32 v[60:61], v[42:43], v[60:61] op_sel_hi:[0,1]
	s_waitcnt lgkmcnt(1)
	v_pk_fma_f32 v[30:31], v[52:53], v[60:61], v[30:31]
	v_pk_fma_f32 v[28:29], v[50:51], v[62:63], v[28:29]
	global_store_dwordx4 v[36:37], v[28:31], off offset:-2048 nt
	global_load_dwordx2 v[50:51], v[58:59], off offset:1536
	s_waitcnt vmcnt(0)
	v_lshlrev_b32_e32 v52, 16, v50
	v_and_b32_e32 v53, 0xffff0000, v50
	v_lshlrev_b32_e32 v50, 16, v51
	v_and_b32_e32 v51, 0xffff0000, v51
	v_pk_mul_f32 v[52:53], v[42:43], v[52:53] op_sel_hi:[0,1]
	v_pk_mul_f32 v[50:51], v[42:43], v[50:51] op_sel_hi:[0,1]
	s_waitcnt lgkmcnt(0)
	v_pk_fma_f32 v[26:27], v[56:57], v[50:51], v[26:27]
	v_pk_fma_f32 v[24:25], v[54:55], v[52:53], v[24:25]
	global_store_dwordx4 v[36:37], v[24:27], off offset:-1024 nt
	global_load_dwordx2 v[60:61], v[58:59], off offset:2048
	ds_read_b128 v[50:53], v49 offset:20480
	ds_read_b128 v[54:57], v49 offset:21504
	s_waitcnt vmcnt(0)
	v_lshlrev_b32_e32 v62, 16, v60
	v_and_b32_e32 v63, 0xffff0000, v60
	v_lshlrev_b32_e32 v60, 16, v61
	v_and_b32_e32 v61, 0xffff0000, v61
	v_pk_mul_f32 v[62:63], v[42:43], v[62:63] op_sel_hi:[0,1]
	v_pk_mul_f32 v[60:61], v[42:43], v[60:61] op_sel_hi:[0,1]
	s_waitcnt lgkmcnt(1)
	v_pk_fma_f32 v[6:7], v[52:53], v[60:61], v[6:7]
	v_pk_fma_f32 v[4:5], v[50:51], v[62:63], v[4:5]
	global_store_dwordx4 v[36:37], v[4:7], off nt
	global_load_dwordx2 v[50:51], v[58:59], off offset:2560
	s_waitcnt vmcnt(0)
	v_lshlrev_b32_e32 v52, 16, v50
	v_and_b32_e32 v53, 0xffff0000, v50
	v_lshlrev_b32_e32 v50, 16, v51
	v_and_b32_e32 v51, 0xffff0000, v51
	v_pk_mul_f32 v[52:53], v[42:43], v[52:53] op_sel_hi:[0,1]
	v_pk_mul_f32 v[50:51], v[42:43], v[50:51] op_sel_hi:[0,1]
	s_waitcnt lgkmcnt(0)
	v_pk_fma_f32 v[10:11], v[56:57], v[50:51], v[10:11]
	v_pk_fma_f32 v[8:9], v[54:55], v[52:53], v[8:9]
	global_store_dwordx4 v[36:37], v[8:11], off offset:1024 nt
	global_load_dwordx2 v[60:61], v[58:59], off offset:3072
	ds_read_b128 v[50:53], v49 offset:22528
	ds_read_b128 v[54:57], v49 offset:23552
	s_waitcnt vmcnt(0)
	v_lshlrev_b32_e32 v62, 16, v60
	v_and_b32_e32 v63, 0xffff0000, v60
	v_lshlrev_b32_e32 v60, 16, v61
	v_and_b32_e32 v61, 0xffff0000, v61
	v_pk_mul_f32 v[62:63], v[42:43], v[62:63] op_sel_hi:[0,1]
	v_pk_mul_f32 v[60:61], v[42:43], v[60:61] op_sel_hi:[0,1]
	s_waitcnt lgkmcnt(1)
; __device__ __forceinline__ float wave_sum(float v) {
; #pragma unroll
;     for (int o = 1; o < 64; o <<= 1) v += __shfl_xor(v, o);
;     return v;
; template <bool POST, bool PRE>
; __device__ __forceinline__ void row_core(const Params& P, const RowCfg& c, LAS float* vA, LAS float* vB, LAS float* vP, const bf16_t* RAW, const float* SSQ, bf16_t* H, int row, int lane, f32x4 (&v)[8]) {
;     ...
;     if (PRE) {
;         float s2 = 0.f;
; #pragma unroll
;         for (int j = 0; j < 8; ++j) s2 += (v[j][0] * v[j][0] + v[j][1] * v[j][1]) + (v[j][2] * v[j][2] + v[j][3] * v[j][3]);
;         s2 = wave_sum(s2);
;         const float rstd2 = rsqrtf(s2 * (1.0f / DM) + EPS);
	v_pk_fma_f32 v[18:19], v[52:53], v[60:61], v[18:19]
	v_pk_fma_f32 v[16:17], v[50:51], v[62:63], v[16:17]
	global_store_dwordx4 v[36:37], v[16:19], off offset:2048 nt
	global_load_dwordx2 v[50:51], v[58:59], off offset:3584
	v_mov_b32_e32 v58, v21
	v_mov_b32_e32 v62, v23
	v_mov_b32_e32 v59, v13
	v_mov_b32_e32 v63, v15
	v_mov_b32_e32 v52, v20
	v_mov_b32_e32 v60, v22
	v_mov_b32_e32 v53, v12
	v_mov_b32_e32 v61, v14
	v_pk_mul_f32 v[58:59], v[58:59], v[58:59]
	v_pk_mul_f32 v[62:63], v[62:63], v[62:63]
	v_pk_fma_f32 v[52:53], v[52:53], v[52:53], v[58:59]
	v_pk_fma_f32 v[58:59], v[60:61], v[60:61], v[62:63]
	v_pk_mul_f32 v[60:61], v[28:29], v[28:29]
	v_pk_add_f32 v[52:53], v[52:53], v[58:59]
	v_pk_mul_f32 v[58:59], v[30:31], v[30:31]
	v_pk_add_f32 v[52:53], v[52:53], v[52:53] op_sel:[0,1] op_sel_hi:[1,0]
	v_pk_mov_b32 v[62:63], v[60:61], v[58:59] op_sel:[1,0]
	v_mov_b32_e32 v61, v59
	v_pk_add_f32 v[58:59], v[62:63], v[60:61]
	v_mul_f32_e32 v60, v25, v25
	v_mul_f32_e32 v62, v27, v27
	v_pk_add_f32 v[58:59], v[58:59], v[58:59] op_sel:[0,1] op_sel_hi:[1,0]
	v_pk_fma_f32 v[60:61], v[24:25], v[24:25], v[60:61] op_sel_hi:[1,1,0]
	v_pk_fma_f32 v[62:63], v[26:27], v[26:27], v[62:63] op_sel_hi:[1,1,0]
	v_mul_f32_e32 v53, v4, v4
	v_mul_f32_e32 v59, v5, v5
	v_mul_f32_e32 v61, v6, v6
	v_mul_f32_e32 v63, v7, v7
	v_pk_add_f32 v[52:53], v[52:53], v[58:59]
	v_pk_add_f32 v[58:59], v[60:61], v[62:63]
	v_pk_mul_f32 v[60:61], v[8:9], v[8:9]
	v_pk_add_f32 v[52:53], v[52:53], v[58:59]
	v_pk_mul_f32 v[58:59], v[10:11], v[10:11]
	v_pk_add_f32 v[52:53], v[52:53], v[52:53] op_sel:[0,1] op_sel_hi:[1,0]
	v_pk_mov_b32 v[62:63], v[60:61], v[58:59] op_sel:[1,0]
	v_mov_b32_e32 v61, v59
	v_pk_add_f32 v[58:59], v[62:63], v[60:61]
	v_mul_f32_e32 v60, v17, v17
	v_mul_f32_e32 v62, v19, v19
	v_pk_add_f32 v[58:59], v[58:59], v[58:59] op_sel:[0,1] op_sel_hi:[1,0]
	v_pk_fma_f32 v[60:61], v[16:17], v[16:17], v[60:61] op_sel_hi:[1,1,0]
	v_pk_fma_f32 v[62:63], v[18:19], v[18:19], v[62:63] op_sel_hi:[1,1,0]
	s_waitcnt vmcnt(0)
	v_lshlrev_b32_e32 v64, 16, v50
	v_and_b32_e32 v65, 0xffff0000, v50
	v_lshlrev_b32_e32 v50, 16, v51
	v_and_b32_e32 v51, 0xffff0000, v51
	v_pk_mul_f32 v[64:65], v[42:43], v[64:65] op_sel_hi:[0,1]
	v_pk_mul_f32 v[50:51], v[42:43], v[50:51] op_sel_hi:[0,1]
	s_waitcnt lgkmcnt(0)
	v_pk_fma_f32 v[2:3], v[56:57], v[50:51], v[2:3]
	v_pk_fma_f32 v[0:1], v[54:55], v[64:65], v[0:1]
	v_mul_f32_e32 v61, v2, v2
	v_mul_f32_e32 v53, v0, v0
	v_mul_f32_e32 v59, v1, v1
	v_mul_f32_e32 v63, v3, v3
	v_pk_add_f32 v[50:51], v[52:53], v[58:59]
	v_pk_add_f32 v[52:53], v[60:61], v[62:63]
	s_nop 0
	v_pk_add_f32 v[50:51], v[50:51], v[52:53]
	s_nop 0
	v_add_f32_e32 v42, v50, v51
	s_nop 1
	v_add_f32_dpp v42, v42, v42 quad_perm:[1,0,3,2] row_mask:0xf bank_mask:0xf
	s_nop 1
	v_add_f32_dpp v42, v42, v42 quad_perm:[2,3,0,1] row_mask:0xf bank_mask:0xf
	s_nop 1
	v_add_f32_dpp v42, v42, v42 row_half_mirror row_mask:0xf bank_mask:0xf
	s_nop 1
	v_add_f32_dpp v42, v42, v42 row_mirror row_mask:0xf bank_mask:0xf
	ds_bpermute_b32 v50, v47, v42
	s_waitcnt lgkmcnt(0)
	v_add_f32_e32 v42, v42, v50
	ds_bpermute_b32 v50, v48, v42
	s_waitcnt lgkmcnt(0)
	v_add_f32_e32 v42, v42, v50
	v_fmamk_f32 v42, v42, 0x3a000000, v33
	v_mul_f32_e32 v50, 0x4b800000, v42
	v_cmp_gt_f32_e64 s[0:1], s3, v42
	s_nop 1
	v_cndmask_b32_e64 v42, v42, v50, s[0:1]
	v_rsq_f32_e32 v42, v42
	ds_read_b128 v[50:53], v49
	ds_read_b128 v[54:57], v49 offset:8192
	global_store_dwordx4 v[36:37], v[0:3], off offset:3072 nt
	v_lshl_add_u64 v[36:37], v[36:37], 0, s[12:13]
	v_mul_f32_e32 v58, 0x45800000, v42
	v_cndmask_b32_e64 v42, v42, v58, s[0:1]
	v_pk_mul_f32 v[20:21], v[20:21], v[42:43] op_sel_hi:[1,0]
	v_pk_mul_f32 v[22:23], v[22:23], v[42:43] op_sel_hi:[1,0]
	s_waitcnt lgkmcnt(0)
; #define LAS __attribute__((address_space(3)))
; __device__ __forceinline__ unsigned cvt_pk_bf16(float lo, float hi) { unsigned r; asm volatile("v_cvt_pk_bf16_f32 %0, %1, %2" : "=v"(r) : "v"(lo), "v"(hi)); return r; }
; template <bool POST, bool PRE>
; __device__ __forceinline__ void row_core(const Params& P, const RowCfg& c, LAS float* vA, LAS float* vB, LAS float* vP, const bf16_t* RAW, const float* SSQ, bf16_t* H, int row, int lane, f32x4 (&v)[8]) {
;     ...
;         u32x2* hs = (u32x2*)(H + (size_t)row * DM) + lane;
; #pragma unroll
;         for (int j = 0; j < 8; ++j) { const f32x4 a = *(const LAS f32x4*)(vA + j * 256 + lane * 4), b = *(const LAS f32x4*)(vB + j * 256 + lane * 4);
;             v[j] = v[j] * rstd2 * a + b; u32x2 w; w.x = cvt_pk_bf16(v[j][0], v[j][1]); w.y = cvt_pk_bf16(v[j][2], v[j][3]); hs[64 * j] = w; }
	v_pk_fma_f32 v[20:21], v[50:51], v[20:21], v[54:55]
	v_pk_fma_f32 v[22:23], v[52:53], v[22:23], v[56:57]
	v_cvt_pk_bf16_f32 v54, v20, v21
	v_add_co_u32_e64 v40, s[0:1], s9, v40
	v_cvt_pk_bf16_f32 v55, v22, v23
	ds_read_b128 v[20:23], v49 offset:1024
	ds_read_b128 v[50:53], v49 offset:9216
	v_pk_mul_f32 v[12:13], v[12:13], v[42:43] op_sel_hi:[1,0]
	v_pk_mul_f32 v[14:15], v[14:15], v[42:43] op_sel_hi:[1,0]
	v_addc_co_u32_e64 v41, s[0:1], 0, v41, s[0:1]
	s_waitcnt lgkmcnt(0)
	v_pk_fma_f32 v[14:15], v[22:23], v[14:15], v[52:53]
	v_pk_fma_f32 v[12:13], v[20:21], v[12:13], v[50:51]
	global_store_dwordx2 v[40:41], v[54:55], off
	v_cvt_pk_bf16_f32 v50, v12, v13
	v_cvt_pk_bf16_f32 v51, v14, v15
	ds_read_b128 v[12:15], v49 offset:2048
	ds_read_b128 v[20:23], v49 offset:10240
	v_pk_mul_f32 v[28:29], v[28:29], v[42:43] op_sel_hi:[1,0]
	v_pk_mul_f32 v[30:31], v[30:31], v[42:43] op_sel_hi:[1,0]
	global_store_dwordx2 v[40:41], v[50:51], off offset:512
	v_pk_mul_f32 v[24:25], v[24:25], v[42:43] op_sel_hi:[1,0]
	s_waitcnt lgkmcnt(0)
	v_pk_fma_f32 v[14:15], v[14:15], v[30:31], v[22:23]
	v_pk_fma_f32 v[12:13], v[12:13], v[28:29], v[20:21]
	v_pk_mul_f32 v[26:27], v[26:27], v[42:43] op_sel_hi:[1,0]
	v_cvt_pk_bf16_f32 v28, v12, v13
	v_cvt_pk_bf16_f32 v29, v14, v15
	ds_read_b128 v[12:15], v49 offset:3072
	ds_read_b128 v[20:23], v49 offset:11264
	global_store_dwordx2 v[40:41], v[28:29], off offset:1024
	v_pk_mul_f32 v[4:5], v[4:5], v[42:43] op_sel_hi:[1,0]
	v_pk_mul_f32 v[6:7], v[6:7], v[42:43] op_sel_hi:[1,0]
	v_pk_mul_f32 v[8:9], v[8:9], v[42:43] op_sel_hi:[1,0]
	s_waitcnt lgkmcnt(0)
	v_pk_fma_f32 v[14:15], v[14:15], v[26:27], v[22:23]
	v_pk_fma_f32 v[12:13], v[12:13], v[24:25], v[20:21]
	v_pk_mul_f32 v[10:11], v[10:11], v[42:43] op_sel_hi:[1,0]
	v_cvt_pk_bf16_f32 v24, v12, v13
	v_cvt_pk_bf16_f32 v25, v14, v15
	ds_read_b128 v[12:15], v49 offset:4096
	ds_read_b128 v[20:23], v49 offset:12288
	global_store_dwordx2 v[40:41], v[24:25], off offset:1536
	v_pk_mul_f32 v[0:1], v[0:1], v[42:43] op_sel_hi:[1,0]
	v_pk_mul_f32 v[2:3], v[2:3], v[42:43] op_sel_hi:[1,0]
	s_waitcnt lgkmcnt(0)
	v_pk_fma_f32 v[6:7], v[14:15], v[6:7], v[22:23]
	v_pk_fma_f32 v[4:5], v[12:13], v[4:5], v[20:21]
	s_nop 0
	v_cvt_pk_bf16_f32 v20, v4, v5
	v_cvt_pk_bf16_f32 v21, v6, v7
	ds_read_b128 v[4:7], v49 offset:5120
	ds_read_b128 v[12:15], v49 offset:13312
	global_store_dwordx2 v[40:41], v[20:21], off offset:2048
	s_waitcnt lgkmcnt(0)
	v_pk_fma_f32 v[6:7], v[10:11], v[6:7], v[14:15]
	v_pk_fma_f32 v[4:5], v[8:9], v[4:5], v[12:13]
	v_pk_mul_f32 v[14:15], v[16:17], v[42:43] op_sel_hi:[1,0]
	v_cvt_pk_bf16_f32 v12, v4, v5
	v_cvt_pk_bf16_f32 v13, v6, v7
	ds_read_b128 v[4:7], v49 offset:6144
	ds_read_b128 v[8:11], v49 offset:14336
	v_pk_mul_f32 v[16:17], v[18:19], v[42:43] op_sel_hi:[1,0]
	global_store_dwordx2 v[40:41], v[12:13], off offset:2560
	s_waitcnt lgkmcnt(0)
	v_pk_fma_f32 v[6:7], v[16:17], v[6:7], v[10:11]
	v_pk_fma_f32 v[4:5], v[14:15], v[4:5], v[8:9]
	s_nop 0
	v_cvt_pk_bf16_f32 v12, v4, v5
	v_cvt_pk_bf16_f32 v13, v6, v7
	ds_read_b128 v[4:7], v49 offset:7168
	ds_read_b128 v[8:11], v49 offset:15360
	global_store_dwordx2 v[40:41], v[12:13], off offset:3072
	s_waitcnt lgkmcnt(0)
	v_pk_fma_f32 v[0:1], v[0:1], v[4:5], v[8:9]
	v_pk_fma_f32 v[2:3], v[2:3], v[6:7], v[10:11]
	v_cvt_pk_bf16_f32 v0, v0, v1
	s_nop 0
	v_cvt_pk_bf16_f32 v1, v2, v3
	global_store_dwordx2 v[40:41], v[0:1], off offset:3584
	s_cbranch_scc0 .LBB0_2056
